# LSE written per unit as 512 contiguous bytes ([g][b][h][r*L+pos]) instead of 4-byte pieces of [token][8] rows; P3 reads the same layout; on top of the fused P9
# speedup vs baseline: 1.0025x; 1.0025x over previous
; #define LAS __attribute__((address_space(3)))
; __device__ __forceinline__ void attn_compute(LAS unsigned char* lds, const bf16x8 (&qf)[4], const AttnUnit& u, bf16* og, float* lse) {
;     const int tid = threadIdx.x, lane = tid & 63, w = __builtin_amdgcn_readfirstlane(tid >> 6);
;     const int d = 1 << (2 * u.g); const int n = u.n, h = u.h;
;     const unsigned par = (unsigned)((n + 1) & 1) << 15;
;     LAS unsigned char* Ks = lds; LAS unsigned char* Vs = lds + 65536; LAS float* tab = (LAS float*)(lds + LDS_TAB);
;     const int qi = 16 * w + (lane & 15), kg = lane >> 4;
;     const size_t qtok = (size_t)u.b * SEQ + (size_t)(n * 128 + qi) * d + u.r;
;     const int ks0 = w >> 1;
;     const int i15 = lane & 15;
;     f32x4 sc[5][2];
;     const unsigned krow = 8 * (i15 >> 2) + (i15 & 3);
; #pragma unroll
;     for (int kk = 0; kk < 5; ++kk) {
;         const int ks = ks0 + kk;
;         bf16x8 kf[2][4];
; #pragma unroll
;         for (int T = 0; T < 2; ++T)
; #pragma unroll
;             for (int s = 0; s < 4; ++s) kf[T][s] = *(const LAS bf16x8*)(Ks + (off_b(32 * ks + krow + 4 * T, 4 * s + kg) ^ par));
; #pragma unroll
;         for (int T = 0; T < 2; ++T) {
;             f32x4 a = {0.f, 0.f, 0.f, 0.f};
; #pragma unroll
;             for (int s = 0; s < 4; ++s) a = __builtin_amdgcn_mfma_f32_16x16x32_bf16(kf[T][s], qf[s], a, 0, 0, 0);
;             sc[kk][T] = a;
;         }
;     }
.LBB0_151:
	s_bfe_u32 s76, s11, 0x30005
	s_sub_i32 s11, 5, s8
	s_lshr_b32 s11, s63, s11
	s_cmp_eq_u32 s10, 1
	s_cselect_b32 s30, s33, s47
	s_cselect_b32 s31, s46, s64
	s_cmp_eq_u32 s10, 0
	v_readfirstlane_b32 s85, v178
	s_cselect_b32 s61, s91, s31
	s_cselect_b32 s60, s90, s30
	s_lshr_b32 s86, s85, 2
	s_and_b32 s83, s86, 0x3fffffe0
	s_not_b32 s30, s63
	v_or_b32_e32 v80, s83, v100
	s_lshl_b32 s30, s30, 15
	v_or_b32_e32 v64, v80, v101
	s_and_b32 s77, s30, 0x8000
	v_lshlrev_b32_e32 v72, 8, v64
	v_bitop3_b32 v64, v72, s77, v103 bitop3:0x36
	v_bitop3_b32 v65, v72, s77, v105 bitop3:0x36
	v_add_u32_e32 v64, 0, v64
	v_add_u32_e32 v68, 0, v65
	ds_read_b128 v[64:67], v64
	ds_read_b128 v[68:71], v68
	s_waitcnt lgkmcnt(1)
	v_mfma_f32_16x16x32_bf16 v[64:67], v[64:67], v[60:63], 0
	v_bitop3_b32 v73, v72, s77, v107 bitop3:0x36
	v_bitop3_b32 v72, v72, s77, v109 bitop3:0x36
	v_add_u32_e32 v73, 0, v73
	v_add_u32_e32 v76, 0, v72
	v_or_b32_e32 v80, 4, v80
	ds_read_b128 v[72:75], v73
	ds_read_b128 v[76:79], v76
	v_or_b32_e32 v83, v80, v101
	v_bfe_u32 v80, v80, 2, 2
	s_waitcnt lgkmcnt(2)
	v_mfma_f32_16x16x32_bf16 v[64:67], v[68:71], v[56:59], v[64:67]
	v_bitop3_b32 v85, v80, v99, v102 bitop3:0x36
	v_bitop3_b32 v86, v80, v104, v102 bitop3:0x36
	v_lshlrev_b32_e32 v83, 8, v83
	v_lshlrev_b32_e32 v85, 4, v85
	v_lshlrev_b32_e32 v86, 4, v86
	v_bitop3_b32 v85, v85, s77, v83 bitop3:0x36
	v_bitop3_b32 v86, v86, s77, v83 bitop3:0x36
	v_add_u32_e32 v85, 0, v85
	v_add_u32_e32 v68, 0, v86
	s_waitcnt lgkmcnt(1)
	v_mfma_f32_16x16x32_bf16 v[64:67], v[72:75], v[52:55], v[64:67]
	ds_read_b128 v[86:89], v85
	ds_read_b128 v[134:137], v68
	v_bitop3_b32 v68, v80, v106, v102 bitop3:0x36
	v_lshlrev_b32_e32 v68, 4, v68
	v_bitop3_b32 v72, v68, s77, v83 bitop3:0x36
	s_waitcnt lgkmcnt(2)
	v_mfma_f32_16x16x32_bf16 v[68:71], v[76:79], v[48:51], v[64:67]
	v_bitop3_b32 v76, v80, v108, v102 bitop3:0x36
	v_lshlrev_b32_e32 v76, 4, v76
	v_bitop3_b32 v76, v76, s77, v83 bitop3:0x36
	v_add_u32_e32 v64, 0, v72
	ds_read_b128 v[64:67], v64
	s_waitcnt lgkmcnt(2)
	v_mfma_f32_16x16x32_bf16 v[72:75], v[86:89], v[60:63], 0
	v_add_u32_e32 v76, 0, v76
	ds_read_b128 v[76:79], v76
	s_add_i32 s82, s83, 32
	s_waitcnt lgkmcnt(2)
	v_mfma_f32_16x16x32_bf16 v[72:75], v[134:137], v[56:59], v[72:75]
	v_or_b32_e32 v80, s82, v100
	s_add_i32 s80, s83, 64
	s_add_i32 s79, s83, 0x60
	s_waitcnt lgkmcnt(1)
	v_mfma_f32_16x16x32_bf16 v[64:67], v[64:67], v[52:55], v[72:75]
	s_add_i32 s78, s83, 0x80
	s_ashr_i32 s63, s62, 31
	s_and_b32 s54, s86, 0x3ffffff0
	v_or_b32_e32 v72, v80, v101
	v_lshlrev_b32_e32 v83, 8, v72
	v_bitop3_b32 v72, v83, s77, v103 bitop3:0x36
	v_bitop3_b32 v73, v83, s77, v105 bitop3:0x36
	s_waitcnt lgkmcnt(0)
	v_mfma_f32_16x16x32_bf16 v[64:67], v[76:79], v[48:51], v[64:67]
	v_add_u32_e32 v72, 0, v72
	v_add_u32_e32 v76, 0, v73
	ds_read_b128 v[72:75], v72
	ds_read_b128 v[76:79], v76
	s_waitcnt lgkmcnt(1)
	v_mfma_f32_16x16x32_bf16 v[72:75], v[72:75], v[60:63], 0
	v_bitop3_b32 v85, v83, s77, v107 bitop3:0x36
	v_bitop3_b32 v83, v83, s77, v109 bitop3:0x36
	v_add_u32_e32 v85, 0, v85
	v_add_u32_e32 v83, 0, v83
	v_or_b32_e32 v80, 4, v80
	ds_read_b128 v[86:89], v85
	ds_read_b128 v[134:137], v83
	v_or_b32_e32 v83, v80, v101
	v_bfe_u32 v80, v80, 2, 2
	s_waitcnt lgkmcnt(2)
	v_mfma_f32_16x16x32_bf16 v[72:75], v[76:79], v[56:59], v[72:75]
	v_bitop3_b32 v85, v80, v99, v102 bitop3:0x36
	v_bitop3_b32 v133, v80, v104, v102 bitop3:0x36
	v_lshlrev_b32_e32 v83, 8, v83
	v_lshlrev_b32_e32 v85, 4, v85
	v_lshlrev_b32_e32 v133, 4, v133
	v_bitop3_b32 v85, v85, s77, v83 bitop3:0x36
	v_bitop3_b32 v133, v133, s77, v83 bitop3:0x36
	v_add_u32_e32 v85, 0, v85
	v_add_u32_e32 v76, 0, v133
	s_waitcnt lgkmcnt(1)
	v_mfma_f32_16x16x32_bf16 v[72:75], v[86:89], v[52:55], v[72:75]
	ds_read_b128 v[138:141], v85
	ds_read_b128 v[142:145], v76
	v_bitop3_b32 v76, v80, v106, v102 bitop3:0x36
	v_lshlrev_b32_e32 v76, 4, v76
	v_bitop3_b32 v85, v76, s77, v83 bitop3:0x36
	s_waitcnt lgkmcnt(2)
	v_mfma_f32_16x16x32_bf16 v[76:79], v[134:137], v[48:51], v[72:75]
	v_bitop3_b32 v80, v80, v108, v102 bitop3:0x36
	v_lshlrev_b32_e32 v80, 4, v80
	v_bitop3_b32 v80, v80, s77, v83 bitop3:0x36
	v_add_u32_e32 v72, 0, v85
	ds_read_b128 v[72:75], v72
	s_waitcnt lgkmcnt(2)
	v_mfma_f32_16x16x32_bf16 v[86:89], v[138:141], v[60:63], 0
	v_add_u32_e32 v80, 0, v80
	ds_read_b128 v[134:137], v80
	v_or_b32_e32 v80, s80, v100
	s_waitcnt lgkmcnt(2)
	v_mfma_f32_16x16x32_bf16 v[86:89], v[142:145], v[56:59], v[86:89]
	v_or_b32_e32 v83, v80, v101
	v_lshlrev_b32_e32 v83, 8, v83
	v_bitop3_b32 v85, v83, s77, v103 bitop3:0x36
	s_waitcnt lgkmcnt(1)
	v_mfma_f32_16x16x32_bf16 v[72:75], v[72:75], v[52:55], v[86:89]
	v_add_u32_e32 v85, 0, v85
	v_or_b32_e32 v80, 4, v80
	s_lshl_b64 s[62:63], s[62:63], 12
	v_bitop3_b32 v86, v83, s77, v105 bitop3:0x36
	s_waitcnt lgkmcnt(0)
	v_mfma_f32_16x16x32_bf16 v[72:75], v[134:137], v[48:51], v[72:75]
	v_add_u32_e32 v133, 0, v86
	ds_read_b128 v[86:89], v85
	ds_read_b128 v[134:137], v133
	v_bitop3_b32 v85, v83, s77, v107 bitop3:0x36
	s_waitcnt lgkmcnt(1)
	v_mfma_f32_16x16x32_bf16 v[86:89], v[86:89], v[60:63], 0
	v_bitop3_b32 v83, v83, s77, v109 bitop3:0x36
	v_add_u32_e32 v85, 0, v85
	v_add_u32_e32 v83, 0, v83
	ds_read_b128 v[138:141], v85
	ds_read_b128 v[142:145], v83
	v_or_b32_e32 v83, v80, v101
	v_bfe_u32 v80, v80, 2, 2
	v_bitop3_b32 v85, v80, v99, v102 bitop3:0x36
	s_waitcnt lgkmcnt(2)
	v_mfma_f32_16x16x32_bf16 v[86:89], v[134:137], v[56:59], v[86:89]
	v_lshlrev_b32_e32 v83, 8, v83
	v_lshlrev_b32_e32 v85, 4, v85
	v_bitop3_b32 v133, v80, v104, v102 bitop3:0x36
	v_bitop3_b32 v85, v85, s77, v83 bitop3:0x36
	v_lshlrev_b32_e32 v133, 4, v133
	v_add_u32_e32 v85, 0, v85
	v_bitop3_b32 v133, v133, s77, v83 bitop3:0x36
	v_add_u32_e32 v133, 0, v133
	ds_read_b128 v[134:137], v85
	ds_read_b128 v[146:149], v133
	s_waitcnt lgkmcnt(3)
; #define LAS __attribute__((address_space(3)))
; __device__ __forceinline__ void attn_compute(LAS unsigned char* lds, const bf16x8 (&qf)[4], const AttnUnit& u, bf16* og, float* lse) {
;     ...
;     for (int kk = 0; kk < 5; ++kk) {
;         const int ks = ks0 + kk;
;         bf16x8 kf[2][4];
; #pragma unroll
;         for (int T = 0; T < 2; ++T)
; #pragma unroll
;             for (int s = 0; s < 4; ++s) kf[T][s] = *(const LAS bf16x8*)(Ks + (off_b(32 * ks + krow + 4 * T, 4 * s + kg) ^ par));
; #pragma unroll
;         for (int T = 0; T < 2; ++T) {
;             f32x4 a = {0.f, 0.f, 0.f, 0.f};
; #pragma unroll
;             for (int s = 0; s < 4; ++s) a = __builtin_amdgcn_mfma_f32_16x16x32_bf16(kf[T][s], qf[s], a, 0, 0, 0);
;             sc[kk][T] = a;
;         }
;     }
;     float tb[5][2][4];
;     { const LAS float* tp = tab + (31 - 16 * (w & 1) - i15 + 8 * kg);
; #pragma unroll
;       for (int kk = 0; kk < 5; ++kk)
; #pragma unroll
;           for (int T = 0; T < 2; ++T)
; #pragma unroll
;               for (int jj = 0; jj < 4; ++jj) tb[kk][T][jj] = tp[32 * kk + 4 * T + jj]; }
	v_mfma_f32_16x16x32_bf16 v[86:89], v[138:141], v[52:55], v[86:89]
	v_bitop3_b32 v85, v80, v106, v102 bitop3:0x36
	v_lshlrev_b32_e32 v85, 4, v85
	v_bitop3_b32 v85, v85, s77, v83 bitop3:0x36
	v_add_u32_e32 v85, 0, v85
	s_waitcnt lgkmcnt(2)
	v_mfma_f32_16x16x32_bf16 v[138:141], v[142:145], v[48:51], v[86:89]
	v_bitop3_b32 v80, v80, v108, v102 bitop3:0x36
	v_lshlrev_b32_e32 v80, 4, v80
	v_bitop3_b32 v80, v80, s77, v83 bitop3:0x36
	ds_read_b128 v[86:89], v85
	s_waitcnt lgkmcnt(2)
	v_mfma_f32_16x16x32_bf16 v[134:137], v[134:137], v[60:63], 0
	v_add_u32_e32 v80, 0, v80
	ds_read_b128 v[142:145], v80
	v_or_b32_e32 v80, s79, v100
	s_waitcnt lgkmcnt(2)
	v_mfma_f32_16x16x32_bf16 v[134:137], v[146:149], v[56:59], v[134:137]
	v_or_b32_e32 v83, v80, v101
	v_lshlrev_b32_e32 v83, 8, v83
	v_bitop3_b32 v85, v83, s77, v103 bitop3:0x36
	s_waitcnt lgkmcnt(1)
	v_mfma_f32_16x16x32_bf16 v[86:89], v[86:89], v[52:55], v[134:137]
	v_add_u32_e32 v85, 0, v85
	v_or_b32_e32 v80, 4, v80
	s_andn2_b32 s30, 16, s86
	s_waitcnt lgkmcnt(0)
	v_mfma_f32_16x16x32_bf16 v[134:137], v[142:145], v[48:51], v[86:89]
	s_cmp_eq_u32 s84, 0
	s_nop 1
	v_bitop3_b32 v86, v83, s77, v105 bitop3:0x36
	v_add_u32_e32 v133, 0, v86
	ds_read_b128 v[86:89], v85
	ds_read_b128 v[142:145], v133
	s_waitcnt lgkmcnt(1)
	v_mfma_f32_16x16x32_bf16 v[86:89], v[86:89], v[60:63], 0
	v_bitop3_b32 v85, v83, s77, v107 bitop3:0x36
	v_bitop3_b32 v83, v83, s77, v109 bitop3:0x36
	v_add_u32_e32 v85, 0, v85
	v_add_u32_e32 v83, 0, v83
	ds_read_b128 v[146:149], v85
	ds_read_b128 v[150:153], v83
	v_or_b32_e32 v83, v80, v101
	v_bfe_u32 v80, v80, 2, 2
	v_bitop3_b32 v85, v80, v99, v102 bitop3:0x36
	s_waitcnt lgkmcnt(2)
	v_mfma_f32_16x16x32_bf16 v[86:89], v[142:145], v[56:59], v[86:89]
	v_lshlrev_b32_e32 v83, 8, v83
	v_lshlrev_b32_e32 v85, 4, v85
	v_bitop3_b32 v133, v80, v104, v102 bitop3:0x36
	v_bitop3_b32 v85, v85, s77, v83 bitop3:0x36
	v_lshlrev_b32_e32 v133, 4, v133
	v_add_u32_e32 v85, 0, v85
	v_bitop3_b32 v133, v133, s77, v83 bitop3:0x36
	v_add_u32_e32 v133, 0, v133
	ds_read_b128 v[142:145], v85
	ds_read_b128 v[154:157], v133
	s_waitcnt lgkmcnt(3)
	v_mfma_f32_16x16x32_bf16 v[86:89], v[146:149], v[52:55], v[86:89]
	v_bitop3_b32 v85, v80, v106, v102 bitop3:0x36
	v_lshlrev_b32_e32 v85, 4, v85
	v_bitop3_b32 v85, v85, s77, v83 bitop3:0x36
	v_add_u32_e32 v85, 0, v85
	s_waitcnt lgkmcnt(2)
	v_mfma_f32_16x16x32_bf16 v[146:149], v[150:153], v[48:51], v[86:89]
	v_bitop3_b32 v80, v80, v108, v102 bitop3:0x36
	v_lshlrev_b32_e32 v80, 4, v80
	v_bitop3_b32 v80, v80, s77, v83 bitop3:0x36
	ds_read_b128 v[86:89], v85
	s_waitcnt lgkmcnt(2)
	v_mfma_f32_16x16x32_bf16 v[142:145], v[142:145], v[60:63], 0
	v_add_u32_e32 v80, 0, v80
	ds_read_b128 v[150:153], v80
	v_or_b32_e32 v80, s78, v100
	s_waitcnt lgkmcnt(2)
	v_mfma_f32_16x16x32_bf16 v[142:145], v[154:157], v[56:59], v[142:145]
	v_or_b32_e32 v83, v80, v101
	v_lshlrev_b32_e32 v83, 8, v83
	v_bitop3_b32 v85, v83, s77, v103 bitop3:0x36
	s_waitcnt lgkmcnt(1)
	v_mfma_f32_16x16x32_bf16 v[86:89], v[86:89], v[52:55], v[142:145]
	v_add_u32_e32 v85, 0, v85
	v_or_b32_e32 v80, 4, v80
	s_waitcnt lgkmcnt(0)
	v_mfma_f32_16x16x32_bf16 v[142:145], v[150:153], v[48:51], v[86:89]
	s_nop 3
	v_bitop3_b32 v86, v83, s77, v105 bitop3:0x36
	v_add_u32_e32 v133, 0, v86
	ds_read_b128 v[86:89], v85
	ds_read_b128 v[150:153], v133
	s_waitcnt lgkmcnt(1)
	v_mfma_f32_16x16x32_bf16 v[86:89], v[86:89], v[60:63], 0
	v_bitop3_b32 v85, v83, s77, v107 bitop3:0x36
	v_bitop3_b32 v83, v83, s77, v109 bitop3:0x36
	v_add_u32_e32 v85, 0, v85
	v_add_u32_e32 v83, 0, v83
	ds_read_b128 v[154:157], v85
	ds_read_b128 v[158:161], v83
	v_or_b32_e32 v83, v80, v101
	v_bfe_u32 v80, v80, 2, 2
	v_bitop3_b32 v85, v80, v99, v102 bitop3:0x36
	s_waitcnt lgkmcnt(2)
	v_mfma_f32_16x16x32_bf16 v[86:89], v[150:153], v[56:59], v[86:89]
	v_lshlrev_b32_e32 v83, 8, v83
	v_lshlrev_b32_e32 v85, 4, v85
	v_bitop3_b32 v133, v80, v104, v102 bitop3:0x36
	v_bitop3_b32 v85, v85, s77, v83 bitop3:0x36
	v_lshlrev_b32_e32 v133, 4, v133
	v_add_u32_e32 v85, 0, v85
	v_bitop3_b32 v133, v133, s77, v83 bitop3:0x36
	v_add_u32_e32 v133, 0, v133
	ds_read_b128 v[150:153], v85
	ds_read_b128 v[162:165], v133
	s_waitcnt lgkmcnt(3)
	v_mfma_f32_16x16x32_bf16 v[86:89], v[154:157], v[52:55], v[86:89]
	v_bitop3_b32 v85, v80, v106, v102 bitop3:0x36
	v_lshlrev_b32_e32 v85, 4, v85
	v_bitop3_b32 v85, v85, s77, v83 bitop3:0x36
	v_add_u32_e32 v85, 0, v85
	s_waitcnt lgkmcnt(2)
	v_mfma_f32_16x16x32_bf16 v[154:157], v[158:161], v[48:51], v[86:89]
	v_bitop3_b32 v80, v80, v108, v102 bitop3:0x36
	v_lshlrev_b32_e32 v80, 4, v80
	v_bitop3_b32 v80, v80, s77, v83 bitop3:0x36
	ds_read_b128 v[86:89], v85
	s_waitcnt lgkmcnt(2)
	v_mfma_f32_16x16x32_bf16 v[60:63], v[150:153], v[60:63], 0
	v_add_u32_e32 v80, 0, v80
	s_waitcnt lgkmcnt(1)
	v_mfma_f32_16x16x32_bf16 v[56:59], v[162:165], v[56:59], v[60:63]
	s_nop 4
	ds_read_b128 v[60:63], v80
	s_waitcnt lgkmcnt(1)
	v_mfma_f32_16x16x32_bf16 v[52:55], v[86:89], v[52:55], v[56:59]
	s_waitcnt lgkmcnt(0)
	v_mfma_f32_16x16x32_bf16 v[52:55], v[60:63], v[48:51], v[52:55]
	v_sub_u32_e32 v48, s30, v92
	v_lshl_add_u32 v48, v48, 2, v110
	s_cselect_b64 s[30:31], -1, 0
	s_cmpk_lt_u32 s85, 0x200
	ds_read2_b32 v[56:57], v48 offset0:15 offset1:16
	ds_read2_b32 v[58:59], v48 offset0:17 offset1:18
	ds_read2_b32 v[60:61], v48 offset0:19 offset1:20
	ds_read2_b32 v[62:63], v48 offset0:21 offset1:22
	ds_read2_b32 v[150:151], v48 offset0:47 offset1:48
	ds_read2_b32 v[152:153], v48 offset0:49 offset1:50
	ds_read2_b32 v[158:159], v48 offset0:51 offset1:52
	ds_read2_b32 v[160:161], v48 offset0:53 offset1:54
	ds_read2_b32 v[162:163], v48 offset0:79 offset1:80
	ds_read2_b32 v[164:165], v48 offset0:81 offset1:82
	ds_read2_b32 v[166:167], v48 offset0:83 offset1:84
	ds_read2_b32 v[168:169], v48 offset0:85 offset1:86
	ds_read2_b32 v[170:171], v48 offset0:111 offset1:112
	ds_read2_b32 v[172:173], v48 offset0:113 offset1:114
	ds_read2_b32 v[174:175], v48 offset0:115 offset1:116
	ds_read2_b32 v[176:177], v48 offset0:117 offset1:118
	ds_read2_b32 v[88:89], v48 offset0:143 offset1:144
	ds_read2_b32 v[86:87], v48 offset0:145 offset1:146
	ds_read2_b32 v[50:51], v48 offset0:147 offset1:148
	ds_read2_b32 v[48:49], v48 offset0:149 offset1:150
	s_cselect_b64 s[86:87], -1, 0
	s_waitcnt lgkmcnt(14)
; __device__ __forceinline__ void attn_compute(LAS unsigned char* lds, const bf16x8 (&qf)[4], const AttnUnit& u, bf16* og, float* lse) {
;     ...
;     const float SCL = 0.08838834764831845f * 1.4426950408889634f;
;     float mx = -1e30f;
; #pragma unroll
;     for (int kk = 0; kk < 5; ++kk) {
;         const bool dead = (n == 0) && (ks0 + kk < 4);
; #pragma unroll
;         for (int T = 0; T < 2; ++T)
; #pragma unroll
;             for (int jj = 0; jj < 4; ++jj) { float v = sc[kk][T][jj] * SCL + tb[kk][T][jj]; v = dead ? -1e30f : v; sc[kk][T][jj] = v; mx = fmaxf(mx, v); }
;     }
;     mx = fmaxf(mx, __shfl_xor(mx, 16)); mx = fmaxf(mx, __shfl_xor(mx, 32));
	v_fmamk_f32 v56, v68, 0x3e0293ee, v56
	s_and_b64 vcc, s[30:31], s[86:87]
	v_fmac_f32_e32 v57, 0x3e0293ee, v69
	v_cndmask_b32_e32 v56, v56, v131, vcc
	v_cndmask_b32_e32 v57, v57, v131, vcc
	v_fmamk_f32 v58, v70, 0x3e0293ee, v58
	v_fmac_f32_e32 v59, 0x3e0293ee, v71
	v_max3_f32 v68, v56, s74, v57
	v_cndmask_b32_e32 v58, v58, v131, vcc
	v_cndmask_b32_e32 v59, v59, v131, vcc
	v_fmamk_f32 v60, v64, 0x3e0293ee, v60
	v_fmac_f32_e32 v61, 0x3e0293ee, v65
	s_cmpk_lt_u32 s85, 0x180
	v_max3_f32 v68, v68, v58, v59
	v_cndmask_b32_e32 v60, v60, v131, vcc
	v_cndmask_b32_e32 v61, v61, v131, vcc
	v_fmamk_f32 v62, v66, 0x3e0293ee, v62
	v_fmac_f32_e32 v63, 0x3e0293ee, v67
	s_cselect_b64 s[86:87], -1, 0
	v_max3_f32 v64, v68, v60, v61
	v_cndmask_b32_e32 v62, v62, v131, vcc
	v_cndmask_b32_e32 v63, v63, v131, vcc
	v_fmamk_f32 v65, v76, 0x3e0293ee, v150
	s_and_b64 vcc, s[30:31], s[86:87]
	v_fmac_f32_e32 v151, 0x3e0293ee, v77
	v_max3_f32 v64, v64, v62, v63
	v_cndmask_b32_e32 v69, v65, v131, vcc
	v_cndmask_b32_e32 v70, v151, v131, vcc
	v_fmamk_f32 v65, v78, 0x3e0293ee, v152
	v_fmac_f32_e32 v153, 0x3e0293ee, v79
	v_max3_f32 v64, v64, v69, v70
	v_cndmask_b32_e32 v71, v65, v131, vcc
	v_cndmask_b32_e32 v76, v153, v131, vcc
	s_waitcnt lgkmcnt(13)
	v_fmamk_f32 v65, v72, 0x3e0293ee, v158
	v_fmac_f32_e32 v159, 0x3e0293ee, v73
	s_cmpk_lt_u32 s85, 0x100
	v_max3_f32 v64, v64, v71, v76
	v_cndmask_b32_e32 v72, v65, v131, vcc
	v_cndmask_b32_e32 v73, v159, v131, vcc
	s_waitcnt lgkmcnt(12)
	v_fmamk_f32 v65, v74, 0x3e0293ee, v160
	v_fmac_f32_e32 v161, 0x3e0293ee, v75
	s_cselect_b64 s[86:87], -1, 0
	v_max3_f32 v64, v64, v72, v73
	v_cndmask_b32_e32 v74, v65, v131, vcc
	v_cndmask_b32_e32 v75, v161, v131, vcc
	s_waitcnt lgkmcnt(11)
	v_fmamk_f32 v65, v138, 0x3e0293ee, v162
	s_and_b64 vcc, s[30:31], s[86:87]
	v_fmac_f32_e32 v163, 0x3e0293ee, v139
	v_max3_f32 v64, v64, v74, v75
	v_cndmask_b32_e32 v77, v65, v131, vcc
	v_cndmask_b32_e32 v78, v163, v131, vcc
	s_waitcnt lgkmcnt(10)
	v_fmamk_f32 v65, v140, 0x3e0293ee, v164
	v_fmac_f32_e32 v165, 0x3e0293ee, v141
	v_max3_f32 v64, v64, v77, v78
	v_cndmask_b32_e32 v79, v65, v131, vcc
	v_cndmask_b32_e32 v83, v165, v131, vcc
	s_waitcnt lgkmcnt(9)
	v_fmamk_f32 v65, v134, 0x3e0293ee, v166
	v_fmac_f32_e32 v167, 0x3e0293ee, v135
	s_cmpk_lt_u32 s85, 0x80
	v_max3_f32 v64, v64, v79, v83
	v_cndmask_b32_e32 v85, v65, v131, vcc
	v_cndmask_b32_e32 v133, v167, v131, vcc
	s_waitcnt lgkmcnt(8)
	v_fmamk_f32 v65, v136, 0x3e0293ee, v168
	v_fmac_f32_e32 v169, 0x3e0293ee, v137
	s_cselect_b64 s[84:85], -1, 0
	v_max3_f32 v64, v64, v85, v133
	v_cndmask_b32_e32 v134, v65, v131, vcc
	v_cndmask_b32_e32 v135, v169, v131, vcc
	s_waitcnt lgkmcnt(7)
	v_fmamk_f32 v65, v146, 0x3e0293ee, v170
	s_and_b64 vcc, s[30:31], s[84:85]
	v_fmac_f32_e32 v171, 0x3e0293ee, v147
	v_max3_f32 v64, v64, v134, v135
	v_cndmask_b32_e32 v136, v65, v131, vcc
	v_cndmask_b32_e32 v137, v171, v131, vcc
	s_waitcnt lgkmcnt(6)
	v_fmamk_f32 v65, v148, 0x3e0293ee, v172
	v_fmac_f32_e32 v173, 0x3e0293ee, v149
	v_max3_f32 v64, v64, v136, v137
	v_cndmask_b32_e32 v138, v65, v131, vcc
	v_cndmask_b32_e32 v139, v173, v131, vcc
	s_waitcnt lgkmcnt(5)
	v_fmamk_f32 v65, v142, 0x3e0293ee, v174
	v_fmac_f32_e32 v175, 0x3e0293ee, v143
	v_max3_f32 v64, v64, v138, v139
	v_cndmask_b32_e32 v140, v65, v131, vcc
	v_cndmask_b32_e32 v141, v175, v131, vcc
	s_waitcnt lgkmcnt(4)
	v_fmamk_f32 v65, v144, 0x3e0293ee, v176
	v_fmac_f32_e32 v177, 0x3e0293ee, v145
	v_max3_f32 v64, v64, v140, v141
	v_cndmask_b32_e32 v142, v65, v131, vcc
	v_cndmask_b32_e32 v143, v177, v131, vcc
	v_max3_f32 v64, v64, v142, v143
	s_waitcnt lgkmcnt(3)
	v_fmamk_f32 v88, v154, 0x3e0293ee, v88
	v_fmac_f32_e32 v89, 0x3e0293ee, v155
	s_waitcnt lgkmcnt(0)
	v_fmamk_f32 v48, v54, 0x3e0293ee, v48
	v_and_b32_e32 v54, 64, v132
	v_max3_f32 v64, v64, v88, v89
	v_fmamk_f32 v86, v156, 0x3e0293ee, v86
	v_fmac_f32_e32 v87, 0x3e0293ee, v157
	v_fmac_f32_e32 v51, 0x3e0293ee, v53
	v_xor_b32_e32 v53, 16, v132
	v_add_u32_e32 v54, 64, v54
	v_max3_f32 v64, v64, v86, v87
	v_fmamk_f32 v50, v52, 0x3e0293ee, v50
	v_cmp_lt_i32_e32 vcc, v53, v54
	v_max3_f32 v52, v64, v50, v51
	v_fmac_f32_e32 v49, 0x3e0293ee, v55
	v_cndmask_b32_e32 v53, v132, v53, vcc
	v_max3_f32 v52, v52, v48, v49
	v_lshlrev_b32_e32 v144, 2, v53
	ds_bpermute_b32 v53, v144, v52
	s_or_b32 s62, s62, s11
	s_waitcnt lgkmcnt(0)
	v_max_f32_e32 v53, v53, v53
	v_max_f32_e32 v52, v52, v53
	v_xor_b32_e32 v53, 32, v132
	v_cmp_lt_i32_e32 vcc, v53, v54
	v_or_b32_e32 v54, s81, v92
	v_add_u32_e32 v80, s54, v54
	v_cndmask_b32_e32 v53, v132, v53, vcc
	v_lshlrev_b32_e32 v145, 2, v53
	ds_bpermute_b32 v53, v145, v52
	s_waitcnt lgkmcnt(0)
; __device__ __forceinline__ unsigned cvtpk(float lo, float hi) { f32x2_t v = {lo, hi}; bf16x2_t b = __builtin_convertvector(v, bf16x2_t); return __builtin_bit_cast(unsigned, b); }
; __device__ __forceinline__ void attn_compute(LAS unsigned char* lds, const bf16x8 (&qf)[4], const AttnUnit& u, bf16* og, float* lse) {
;     ...
;     float l = 0.f;
;     bf16x8 pf[5];
; #pragma unroll
;     for (int kk = 0; kk < 5; ++kk) {
;         float e[8];
; #pragma unroll
;         for (int T = 0; T < 2; ++T)
; #pragma unroll
;             for (int jj = 0; jj < 4; ++jj) { const float p = __builtin_amdgcn_exp2f(sc[kk][T][jj] - mx); e[4 * T + jj] = p; l += p; }
;         v4u pw; pw.x = cvtpk(e[0], e[1]); pw.y = cvtpk(e[2], e[3]); pw.z = cvtpk(e[4], e[5]); pw.w = cvtpk(e[6], e[7]);
;         pf[kk] = __builtin_bit_cast(bf16x8, pw);
;     }
;     l += __shfl_xor(l, 16); l += __shfl_xor(l, 32);
;     f32x4 o[8];
; #pragma unroll
;     for (int c = 0; c < 8; ++c) o[c] = (f32x4){0.f, 0.f, 0.f, 0.f};
;     const unsigned vbase = (unsigned)(uintptr_t)Vs;
;     const unsigned q4 = (lane & 15) >> 2, p4 = lane & 3;
;     s16x4 vlo[2][8], vhi[2][8];
	v_max_f32_e32 v53, v53, v53
	v_max_f32_e32 v68, v52, v53
	v_sub_f32_e32 v52, v56, v68
	v_exp_f32_e32 v52, v52
	v_sub_f32_e32 v53, v57, v68
	v_exp_f32_e32 v53, v53
	v_sub_f32_e32 v54, v58, v68
	v_exp_f32_e32 v54, v54
	v_sub_f32_e32 v55, v59, v68
	v_exp_f32_e32 v55, v55
	v_sub_f32_e32 v57, v60, v68
	v_add_f32_e32 v56, 0, v52
	v_exp_f32_e32 v57, v57
	v_sub_f32_e32 v58, v61, v68
	v_add_f32_e32 v56, v53, v56
	v_exp_f32_e32 v58, v58
	v_sub_f32_e32 v59, v62, v68
	v_add_f32_e32 v56, v54, v56
	v_exp_f32_e32 v59, v59
	v_sub_f32_e32 v60, v63, v68
	v_add_f32_e32 v56, v55, v56
	v_exp_f32_e32 v60, v60
	v_cvt_pk_bf16_f32 v64, v52, v53
	v_sub_f32_e32 v52, v69, v68
	v_add_f32_e32 v56, v57, v56
	v_exp_f32_e32 v52, v52
	v_sub_f32_e32 v53, v70, v68
	v_add_f32_e32 v56, v58, v56
	v_cvt_pk_bf16_f32 v65, v54, v55
	v_exp_f32_e32 v53, v53
	v_sub_f32_e32 v54, v71, v68
	v_add_f32_e32 v56, v59, v56
	v_exp_f32_e32 v54, v54
	v_sub_f32_e32 v55, v76, v68
	v_add_f32_e32 v56, v60, v56
	v_cvt_pk_bf16_f32 v66, v57, v58
	v_exp_f32_e32 v55, v55
	v_sub_f32_e32 v57, v72, v68
	v_add_f32_e32 v56, v52, v56
	v_exp_f32_e32 v57, v57
	v_sub_f32_e32 v58, v73, v68
	v_cvt_pk_bf16_f32 v67, v59, v60
	v_add_f32_e32 v56, v53, v56
	v_exp_f32_e32 v58, v58
	v_sub_f32_e32 v59, v74, v68
	v_add_f32_e32 v56, v54, v56
	v_exp_f32_e32 v59, v59
	v_sub_f32_e32 v60, v75, v68
	v_add_f32_e32 v56, v55, v56
	v_exp_f32_e32 v63, v60
	v_cvt_pk_bf16_f32 v60, v52, v53
	v_sub_f32_e32 v52, v77, v68
	v_add_f32_e32 v56, v57, v56
	v_exp_f32_e32 v52, v52
	v_sub_f32_e32 v53, v78, v68
	v_add_f32_e32 v56, v58, v56
	v_cvt_pk_bf16_f32 v61, v54, v55
	v_exp_f32_e32 v53, v53
	v_sub_f32_e32 v54, v79, v68
	v_add_f32_e32 v56, v59, v56
	v_exp_f32_e32 v54, v54
	v_sub_f32_e32 v55, v83, v68
	v_add_f32_e32 v56, v63, v56
	v_cvt_pk_bf16_f32 v62, v57, v58
	v_exp_f32_e32 v55, v55
	v_sub_f32_e32 v57, v85, v68
	v_add_f32_e32 v56, v52, v56
	v_exp_f32_e32 v58, v57
	v_sub_f32_e32 v57, v133, v68
	v_cvt_pk_bf16_f32 v63, v59, v63
	v_add_f32_e32 v56, v53, v56
	v_exp_f32_e32 v59, v57
	v_sub_f32_e32 v57, v134, v68
	v_add_f32_e32 v56, v54, v56
	v_exp_f32_e32 v69, v57
	v_sub_f32_e32 v57, v135, v68
	v_add_f32_e32 v56, v55, v56
	v_exp_f32_e32 v70, v57
	v_add_f32_e32 v56, v58, v56
	v_add_f32_e32 v56, v59, v56
	v_add_f32_e32 v56, v69, v56
	v_add_f32_e32 v71, v70, v56
	v_cvt_pk_bf16_f32 v56, v52, v53
	v_sub_f32_e32 v52, v136, v68
	v_exp_f32_e32 v52, v52
	v_sub_f32_e32 v53, v137, v68
	v_cvt_pk_bf16_f32 v57, v54, v55
	v_exp_f32_e32 v53, v53
	v_sub_f32_e32 v54, v138, v68
	v_exp_f32_e32 v54, v54
	v_sub_f32_e32 v55, v139, v68
	v_cvt_pk_bf16_f32 v58, v58, v59
	v_cvt_pk_bf16_f32 v59, v69, v70
	v_exp_f32_e32 v55, v55
	v_add_f32_e32 v69, v52, v71
	v_sub_f32_e32 v70, v140, v68
	v_sub_f32_e32 v71, v141, v68
	v_exp_f32_e32 v70, v70
	v_exp_f32_e32 v71, v71
	v_add_f32_e32 v69, v53, v69
	v_sub_f32_e32 v72, v142, v68
	v_sub_f32_e32 v73, v143, v68
	v_add_f32_e32 v69, v54, v69
	v_exp_f32_e32 v72, v72
	v_exp_f32_e32 v73, v73
	v_add_f32_e32 v69, v55, v69
	v_add_f32_e32 v69, v70, v69
	v_cvt_pk_bf16_f32 v52, v52, v53
	v_cvt_pk_bf16_f32 v53, v54, v55
	v_cvt_pk_bf16_f32 v54, v70, v71
	v_sub_f32_e32 v70, v88, v68
	v_add_f32_e32 v69, v71, v69
	v_exp_f32_e32 v70, v70
	v_sub_f32_e32 v71, v89, v68
	v_add_f32_e32 v69, v72, v69
	v_cvt_pk_bf16_f32 v55, v72, v73
	v_exp_f32_e32 v71, v71
	v_sub_f32_e32 v72, v86, v68
	v_add_f32_e32 v69, v73, v69
	v_exp_f32_e32 v72, v72
	v_sub_f32_e32 v73, v87, v68
	v_exp_f32_e32 v73, v73
	v_sub_f32_e32 v50, v50, v68
	v_add_f32_e32 v69, v70, v69
	v_exp_f32_e32 v50, v50
	v_sub_f32_e32 v51, v51, v68
	v_add_f32_e32 v69, v71, v69
	v_exp_f32_e32 v51, v51
	v_sub_f32_e32 v48, v48, v68
	v_add_f32_e32 v69, v72, v69
	v_exp_f32_e32 v74, v48
	v_sub_f32_e32 v48, v49, v68
	v_add_f32_e32 v69, v73, v69
	v_exp_f32_e32 v75, v48
	v_add_f32_e32 v48, v50, v69
	v_add_f32_e32 v48, v51, v48
	v_add_f32_e32 v48, v74, v48
	v_add_f32_e32 v69, v75, v48
	v_cvt_pk_bf16_f32 v48, v70, v71
	v_or_b32_e32 v71, s83, v111
	v_lshl_or_b32 v83, v71, 8, v114
	v_or_b32_e32 v71, 4, v71
	v_bitop3_b32 v133, v83, s77, v121 bitop3:0x36
	v_bfe_u32 v85, v71, 2, 2
	v_add_u32_e32 v133, s73, v133
	ds_read_b64_tr_b16 v[134:135], v133
	v_bitop3_b32 v133, v85, v120, v113 bitop3:0x36
	v_lshl_or_b32 v71, v71, 8, v114
	v_lshlrev_b32_e32 v133, 4, v133
	v_bitop3_b32 v133, v133, s77, v71 bitop3:0x36
	v_add_u32_e32 v133, s73, v133
	ds_read_b64_tr_b16 v[136:137], v133
	v_bitop3_b32 v133, v83, s77, v123 bitop3:0x36
	v_add_u32_e32 v133, s73, v133
	ds_read_b64_tr_b16 v[138:139], v133
	v_bitop3_b32 v133, v85, v122, v113 bitop3:0x36
	v_lshlrev_b32_e32 v133, 4, v133
	v_bitop3_b32 v133, v133, s77, v71 bitop3:0x36
	v_add_u32_e32 v133, s73, v133
	ds_bpermute_b32 v76, v144, v69
	ds_read_b64_tr_b16 v[140:141], v133
	v_bitop3_b32 v133, v83, s77, v126 bitop3:0x36
	v_add_u32_e32 v133, s73, v133
	ds_read_b64_tr_b16 v[142:143], v133
	v_bitop3_b32 v133, v85, v124, v113 bitop3:0x36
	v_lshlrev_b32_e32 v133, 4, v133
	v_bitop3_b32 v133, v133, s77, v71 bitop3:0x36
	s_waitcnt lgkmcnt(2)
; #define ATT_VLOAD(kk_, buf_) do { const unsigned r0_ = 32 * (ks0 + (kk_)) + 8 * kg + q4; _Pragma("unroll") for (int c = 0; c < 8; ++c) { \
;         vlo[buf_][c] = vtr(vbase + ((off_b(r0_, 2 * c + (p4 >> 1)) + 8 * (p4 & 1)) ^ par)); vhi[buf_][c] = vtr(vbase + ((off_b(r0_ + 4, 2 * c + (p4 >> 1)) + 8 * (p4 & 1)) ^ par)); } } while (0)
; __device__ __forceinline__ void attn_compute(LAS unsigned char* lds, const bf16x8 (&qf)[4], const AttnUnit& u, bf16* og, float* lse) {
;     ...
;     l += __shfl_xor(l, 16); l += __shfl_xor(l, 32);
;     f32x4 o[8];
; #pragma unroll
;     for (int c = 0; c < 8; ++c) o[c] = (f32x4){0.f, 0.f, 0.f, 0.f};
;     const unsigned vbase = (unsigned)(uintptr_t)Vs;
;     const unsigned q4 = (lane & 15) >> 2, p4 = lane & 3;
;     s16x4 vlo[2][8], vhi[2][8];
;     ...
;     ATT_VLOAD(0, 0);
; #pragma unroll
;     for (int kk = 0; kk < 5; ++kk) {
;         if (kk < 4) ATT_VLOAD(kk + 1, (kk + 1) & 1);
; #pragma unroll
;         for (int c = 0; c < 8; ++c) {
;             const s16x4 lo = vlo[kk & 1][c], hi = vhi[kk & 1][c];
;             const bf16x8 vf = (bf16x8){lo[0], lo[1], lo[2], lo[3], hi[0], hi[1], hi[2], hi[3]};
;             o[c] = __builtin_amdgcn_mfma_f32_16x16x32_bf16(vf, pf[kk], o[c], 0, 0, 0);
;         }
;     }
	v_add_f32_e32 v69, v69, v76
	v_add_u32_e32 v133, s73, v133
	v_cvt_pk_bf16_f32 v49, v72, v73
	ds_bpermute_b32 v70, v145, v69
	v_bitop3_b32 v72, v83, s77, v115 bitop3:0x36
	v_bitop3_b32 v76, v83, s77, v117 bitop3:0x36
	v_bitop3_b32 v86, v83, s77, v119 bitop3:0x36
	ds_read_b64_tr_b16 v[144:145], v133
	v_bitop3_b32 v133, v83, s77, v128 bitop3:0x36
	v_bitop3_b32 v83, v83, s77, v130 bitop3:0x36
	v_add_u32_e32 v133, s73, v133
	v_add_u32_e32 v83, s73, v83
	v_cvt_pk_bf16_f32 v50, v50, v51
	v_cvt_pk_bf16_f32 v51, v74, v75
	v_bitop3_b32 v74, v85, v112, v113 bitop3:0x36
	v_bitop3_b32 v78, v85, v116, v113 bitop3:0x36
	v_bitop3_b32 v88, v85, v118, v113 bitop3:0x36
	ds_read_b64_tr_b16 v[146:147], v133
	v_bitop3_b32 v133, v85, v127, v113 bitop3:0x36
	ds_read_b64_tr_b16 v[150:151], v83
	v_bitop3_b32 v83, v85, v129, v113 bitop3:0x36
	v_lshlrev_b32_e32 v74, 4, v74
	v_lshlrev_b32_e32 v78, 4, v78
	v_lshlrev_b32_e32 v88, 4, v88
	v_lshlrev_b32_e32 v133, 4, v133
	v_lshlrev_b32_e32 v83, 4, v83
	v_bitop3_b32 v74, v74, s77, v71 bitop3:0x36
	v_bitop3_b32 v78, v78, s77, v71 bitop3:0x36
	v_bitop3_b32 v88, v88, s77, v71 bitop3:0x36
	v_bitop3_b32 v133, v133, s77, v71 bitop3:0x36
	v_bitop3_b32 v71, v83, s77, v71 bitop3:0x36
	v_add_u32_e32 v71, s73, v71
	ds_read_b64_tr_b16 v[152:153], v71
	v_or_b32_e32 v71, s82, v111
	v_add_u32_e32 v133, s73, v133
	v_lshl_or_b32 v83, v71, 8, v114
	ds_read_b64_tr_b16 v[148:149], v133
	v_or_b32_e32 v71, 4, v71
	v_bitop3_b32 v133, v83, s77, v115 bitop3:0x36
	v_bfe_u32 v85, v71, 2, 2
	v_add_u32_e32 v133, s73, v133
	ds_read_b64_tr_b16 v[154:155], v133
	v_bitop3_b32 v133, v85, v112, v113 bitop3:0x36
	v_lshl_or_b32 v71, v71, 8, v114
	v_lshlrev_b32_e32 v133, 4, v133
	v_bitop3_b32 v133, v133, s77, v71 bitop3:0x36
	v_add_u32_e32 v133, s73, v133
	ds_read_b64_tr_b16 v[156:157], v133
	v_bitop3_b32 v133, v83, s77, v117 bitop3:0x36
	v_add_u32_e32 v133, s73, v133
	ds_read_b64_tr_b16 v[158:159], v133
	v_bitop3_b32 v133, v85, v116, v113 bitop3:0x36
	v_lshlrev_b32_e32 v133, 4, v133
	v_bitop3_b32 v133, v133, s77, v71 bitop3:0x36
	v_add_u32_e32 v133, s73, v133
	ds_read_b64_tr_b16 v[160:161], v133
	v_bitop3_b32 v133, v83, s77, v119 bitop3:0x36
	v_add_u32_e32 v133, s73, v133
	ds_read_b64_tr_b16 v[162:163], v133
	v_bitop3_b32 v133, v85, v118, v113 bitop3:0x36
	v_lshlrev_b32_e32 v133, 4, v133
	v_bitop3_b32 v133, v133, s77, v71 bitop3:0x36
	v_add_u32_e32 v133, s73, v133
	ds_read_b64_tr_b16 v[164:165], v133
	v_bitop3_b32 v133, v83, s77, v121 bitop3:0x36
	v_add_u32_e32 v133, s73, v133
	ds_read_b64_tr_b16 v[166:167], v133
	v_bitop3_b32 v133, v85, v120, v113 bitop3:0x36
	v_lshlrev_b32_e32 v133, 4, v133
	v_bitop3_b32 v133, v133, s77, v71 bitop3:0x36
	v_add_u32_e32 v133, s73, v133
	ds_read_b64_tr_b16 v[168:169], v133
	v_bitop3_b32 v133, v83, s77, v123 bitop3:0x36
	v_add_u32_e32 v133, s73, v133
	ds_read_b64_tr_b16 v[170:171], v133
	v_bitop3_b32 v133, v85, v122, v113 bitop3:0x36
	v_lshlrev_b32_e32 v133, 4, v133
	v_bitop3_b32 v133, v133, s77, v71 bitop3:0x36
	v_add_u32_e32 v133, s73, v133
	ds_read_b64_tr_b16 v[172:173], v133
	v_bitop3_b32 v133, v83, s77, v126 bitop3:0x36
	v_add_u32_e32 v133, s73, v133
	ds_read_b64_tr_b16 v[174:175], v133
	v_bitop3_b32 v133, v85, v124, v113 bitop3:0x36
	v_lshlrev_b32_e32 v133, 4, v133
	v_bitop3_b32 v133, v133, s77, v71 bitop3:0x36
	v_add_u32_e32 v133, s73, v133
	v_add_u32_e32 v72, s73, v72
	v_add_u32_e32 v74, s73, v74
	v_add_u32_e32 v76, s73, v76
	v_add_u32_e32 v78, s73, v78
	v_add_u32_e32 v86, s73, v86
	v_add_u32_e32 v88, s73, v88
	ds_read_b64_tr_b16 v[176:177], v133
	v_bitop3_b32 v133, v83, s77, v128 bitop3:0x36
	v_bitop3_b32 v83, v83, s77, v130 bitop3:0x36
	ds_read_b64_tr_b16 v[72:73], v72
	ds_read_b64_tr_b16 v[74:75], v74
	ds_read_b64_tr_b16 v[76:77], v76
	ds_read_b64_tr_b16 v[78:79], v78
	ds_read_b64_tr_b16 v[86:87], v86
	ds_read_b64_tr_b16 v[88:89], v88
	v_add_u32_e32 v133, s73, v133
	v_add_u32_e32 v83, s73, v83
	ds_read_b64_tr_b16 v[180:181], v133
	v_bitop3_b32 v133, v85, v127, v113 bitop3:0x36
	ds_read_b64_tr_b16 v[184:185], v83
	v_bitop3_b32 v83, v85, v129, v113 bitop3:0x36
	v_lshlrev_b32_e32 v133, 4, v133
	v_lshlrev_b32_e32 v83, 4, v83
	v_bitop3_b32 v133, v133, s77, v71 bitop3:0x36
	v_bitop3_b32 v71, v83, s77, v71 bitop3:0x36
	v_add_u32_e32 v71, s73, v71
	ds_read_b64_tr_b16 v[186:187], v71
	v_or_b32_e32 v71, s80, v111
	v_add_u32_e32 v133, s73, v133
	v_lshl_or_b32 v83, v71, 8, v114
	ds_read_b64_tr_b16 v[182:183], v133
	v_or_b32_e32 v71, 4, v71
	v_bitop3_b32 v133, v83, s77, v115 bitop3:0x36
	v_bfe_u32 v85, v71, 2, 2
	v_add_u32_e32 v133, s73, v133
	s_waitcnt lgkmcnt(8)
	v_mfma_f32_16x16x32_bf16 v[72:75], v[72:75], v[64:67], 0
	v_lshl_or_b32 v71, v71, 8, v114
	s_waitcnt lgkmcnt(6)
	v_mfma_f32_16x16x32_bf16 v[76:79], v[76:79], v[64:67], 0
	s_waitcnt lgkmcnt(4)
; #define ATT_VLOAD(kk_, buf_) do { const unsigned r0_ = 32 * (ks0 + (kk_)) + 8 * kg + q4; _Pragma("unroll") for (int c = 0; c < 8; ++c) { \
;         vlo[buf_][c] = vtr(vbase + ((off_b(r0_, 2 * c + (p4 >> 1)) + 8 * (p4 & 1)) ^ par)); vhi[buf_][c] = vtr(vbase + ((off_b(r0_ + 4, 2 * c + (p4 >> 1)) + 8 * (p4 & 1)) ^ par)); } } while (0)
; __device__ __forceinline__ void attn_compute(LAS unsigned char* lds, const bf16x8 (&qf)[4], const AttnUnit& u, bf16* og, float* lse) {
;     ...
;     ATT_VLOAD(0, 0);
; #pragma unroll
;     for (int kk = 0; kk < 5; ++kk) {
;         if (kk < 4) ATT_VLOAD(kk + 1, (kk + 1) & 1);
; #pragma unroll
;         for (int c = 0; c < 8; ++c) {
;             const s16x4 lo = vlo[kk & 1][c], hi = vhi[kk & 1][c];
;             const bf16x8 vf = (bf16x8){lo[0], lo[1], lo[2], lo[3], hi[0], hi[1], hi[2], hi[3]};
;             o[c] = __builtin_amdgcn_mfma_f32_16x16x32_bf16(vf, pf[kk], o[c], 0, 0, 0);
;         }
;     }
	v_mfma_f32_16x16x32_bf16 v[86:89], v[86:89], v[64:67], 0
	v_mfma_f32_16x16x32_bf16 v[134:137], v[134:137], v[64:67], 0
	v_mfma_f32_16x16x32_bf16 v[138:141], v[138:141], v[64:67], 0
	v_mfma_f32_16x16x32_bf16 v[142:145], v[142:145], v[64:67], 0
	v_mfma_f32_16x16x32_bf16 v[146:149], v[146:149], v[64:67], 0
	v_mfma_f32_16x16x32_bf16 v[64:67], v[150:153], v[64:67], 0
	ds_read_b64_tr_b16 v[150:151], v133
	v_bitop3_b32 v133, v85, v112, v113 bitop3:0x36
	v_lshlrev_b32_e32 v133, 4, v133
	v_bitop3_b32 v133, v133, s77, v71 bitop3:0x36
	v_add_u32_e32 v133, s73, v133
	ds_read_b64_tr_b16 v[152:153], v133
	v_bitop3_b32 v133, v83, s77, v117 bitop3:0x36
	v_add_u32_e32 v133, s73, v133
	ds_read_b64_tr_b16 v[188:189], v133
	v_bitop3_b32 v133, v85, v116, v113 bitop3:0x36
	v_lshlrev_b32_e32 v133, 4, v133
	v_bitop3_b32 v133, v133, s77, v71 bitop3:0x36
	v_add_u32_e32 v133, s73, v133
	ds_read_b64_tr_b16 v[190:191], v133
	v_bitop3_b32 v133, v83, s77, v119 bitop3:0x36
	v_add_u32_e32 v133, s73, v133
	ds_read_b64_tr_b16 v[192:193], v133
	v_bitop3_b32 v133, v85, v118, v113 bitop3:0x36
	v_lshlrev_b32_e32 v133, 4, v133
	v_bitop3_b32 v133, v133, s77, v71 bitop3:0x36
	v_add_u32_e32 v133, s73, v133
	ds_read_b64_tr_b16 v[194:195], v133
	v_bitop3_b32 v133, v83, s77, v121 bitop3:0x36
	v_add_u32_e32 v133, s73, v133
	ds_read_b64_tr_b16 v[196:197], v133
	v_bitop3_b32 v133, v85, v120, v113 bitop3:0x36
	v_lshlrev_b32_e32 v133, 4, v133
	v_bitop3_b32 v133, v133, s77, v71 bitop3:0x36
	v_add_u32_e32 v133, s73, v133
	ds_read_b64_tr_b16 v[198:199], v133
	v_bitop3_b32 v133, v83, s77, v123 bitop3:0x36
	v_add_u32_e32 v133, s73, v133
	ds_read_b64_tr_b16 v[200:201], v133
	v_bitop3_b32 v133, v85, v122, v113 bitop3:0x36
	v_lshlrev_b32_e32 v133, 4, v133
	v_bitop3_b32 v133, v133, s77, v71 bitop3:0x36
	v_add_u32_e32 v133, s73, v133
	ds_read_b64_tr_b16 v[202:203], v133
	v_bitop3_b32 v133, v83, s77, v126 bitop3:0x36
	v_add_u32_e32 v133, s73, v133
	ds_read_b64_tr_b16 v[204:205], v133
	v_bitop3_b32 v133, v85, v124, v113 bitop3:0x36
	v_lshlrev_b32_e32 v133, 4, v133
	v_bitop3_b32 v133, v133, s77, v71 bitop3:0x36
	v_add_u32_e32 v133, s73, v133
	ds_read_b64_tr_b16 v[206:207], v133
	v_bitop3_b32 v133, v83, s77, v128 bitop3:0x36
	v_bitop3_b32 v83, v83, s77, v130 bitop3:0x36
	v_add_u32_e32 v133, s73, v133
	v_add_u32_e32 v83, s73, v83
	v_mfma_f32_16x16x32_bf16 v[72:75], v[154:157], v[60:63], v[72:75]
	ds_read_b64_tr_b16 v[154:155], v133
	v_bitop3_b32 v133, v85, v127, v113 bitop3:0x36
	v_lshlrev_b32_e32 v133, 4, v133
	v_mfma_f32_16x16x32_bf16 v[76:79], v[158:161], v[60:63], v[76:79]
	ds_read_b64_tr_b16 v[158:159], v83
	v_bitop3_b32 v83, v85, v129, v113 bitop3:0x36
	v_lshlrev_b32_e32 v83, 4, v83
	v_bitop3_b32 v133, v133, s77, v71 bitop3:0x36
	v_bitop3_b32 v71, v83, s77, v71 bitop3:0x36
	v_mfma_f32_16x16x32_bf16 v[86:89], v[162:165], v[60:63], v[86:89]
	v_add_u32_e32 v71, s73, v71
	v_add_u32_e32 v133, s73, v133
	ds_read_b64_tr_b16 v[160:161], v71
	v_mfma_f32_16x16x32_bf16 v[134:137], v[166:169], v[60:63], v[134:137]
	ds_read_b64_tr_b16 v[156:157], v133
	v_mfma_f32_16x16x32_bf16 v[138:141], v[170:173], v[60:63], v[138:141]
	v_mfma_f32_16x16x32_bf16 v[142:145], v[174:177], v[60:63], v[142:145]
	s_waitcnt lgkmcnt(14)
	v_mfma_f32_16x16x32_bf16 v[146:149], v[180:183], v[60:63], v[146:149]
	v_mfma_f32_16x16x32_bf16 v[60:63], v[184:187], v[60:63], v[64:67]
	s_nop 2
	v_or_b32_e32 v64, s79, v111
	v_lshl_or_b32 v71, v64, 8, v114
	v_or_b32_e32 v64, 4, v64
	v_bitop3_b32 v133, v71, s77, v117 bitop3:0x36
	v_bfe_u32 v83, v64, 2, 2
	v_add_u32_e32 v133, s73, v133
	ds_read_b64_tr_b16 v[162:163], v133
	v_bitop3_b32 v133, v83, v116, v113 bitop3:0x36
	v_lshl_or_b32 v85, v64, 8, v114
	v_lshlrev_b32_e32 v133, 4, v133
	v_bitop3_b32 v133, v133, s77, v85 bitop3:0x36
	v_add_u32_e32 v133, s73, v133
	ds_read_b64_tr_b16 v[164:165], v133
	v_bitop3_b32 v133, v71, s77, v119 bitop3:0x36
	v_add_u32_e32 v133, s73, v133
	ds_read_b64_tr_b16 v[166:167], v133
	v_bitop3_b32 v133, v83, v118, v113 bitop3:0x36
	v_lshlrev_b32_e32 v133, 4, v133
	v_bitop3_b32 v133, v133, s77, v85 bitop3:0x36
	v_add_u32_e32 v133, s73, v133
	ds_read_b64_tr_b16 v[168:169], v133
	v_bitop3_b32 v133, v71, s77, v121 bitop3:0x36
	v_add_u32_e32 v133, s73, v133
	ds_read_b64_tr_b16 v[170:171], v133
	v_bitop3_b32 v133, v83, v120, v113 bitop3:0x36
	v_lshlrev_b32_e32 v133, 4, v133
	v_bitop3_b32 v133, v133, s77, v85 bitop3:0x36
	v_add_u32_e32 v133, s73, v133
	ds_read_b64_tr_b16 v[172:173], v133
	v_bitop3_b32 v133, v71, s77, v123 bitop3:0x36
	v_add_u32_e32 v133, s73, v133
	ds_read_b64_tr_b16 v[174:175], v133
	v_bitop3_b32 v133, v83, v122, v113 bitop3:0x36
	v_lshlrev_b32_e32 v133, 4, v133
	v_bitop3_b32 v133, v133, s77, v85 bitop3:0x36
	v_add_u32_e32 v133, s73, v133
	ds_read_b64_tr_b16 v[176:177], v133
	v_bitop3_b32 v133, v71, s77, v126 bitop3:0x36
	v_add_u32_e32 v133, s73, v133
	ds_read_b64_tr_b16 v[180:181], v133
	v_bitop3_b32 v133, v83, v124, v113 bitop3:0x36
	v_lshlrev_b32_e32 v133, 4, v133
	v_bitop3_b32 v133, v133, s77, v85 bitop3:0x36
	v_add_u32_e32 v133, s73, v133
	v_bitop3_b32 v64, v71, s77, v115 bitop3:0x36
	ds_read_b64_tr_b16 v[182:183], v133
	v_bitop3_b32 v133, v71, s77, v128 bitop3:0x36
	v_bitop3_b32 v71, v71, s77, v130 bitop3:0x36
	v_add_u32_e32 v71, s73, v71
	v_add_u32_e32 v133, s73, v133
	ds_read_b64_tr_b16 v[184:185], v71
	v_bitop3_b32 v71, v83, v129, v113 bitop3:0x36
	v_mfma_f32_16x16x32_bf16 v[72:75], v[150:153], v[56:59], v[72:75]
	ds_read_b64_tr_b16 v[150:151], v133
	v_bitop3_b32 v133, v83, v127, v113 bitop3:0x36
	v_lshlrev_b32_e32 v71, 4, v71
	v_lshlrev_b32_e32 v133, 4, v133
	v_bitop3_b32 v71, v71, s77, v85 bitop3:0x36
	v_bitop3_b32 v66, v83, v112, v113 bitop3:0x36
	s_waitcnt lgkmcnt(14)
; #define ATT_VLOAD(kk_, buf_) do { const unsigned r0_ = 32 * (ks0 + (kk_)) + 8 * kg + q4; _Pragma("unroll") for (int c = 0; c < 8; ++c) { \
;         vlo[buf_][c] = vtr(vbase + ((off_b(r0_, 2 * c + (p4 >> 1)) + 8 * (p4 & 1)) ^ par)); vhi[buf_][c] = vtr(vbase + ((off_b(r0_ + 4, 2 * c + (p4 >> 1)) + 8 * (p4 & 1)) ^ par)); } } while (0)
; __device__ __forceinline__ void attn_compute(LAS unsigned char* lds, const bf16x8 (&qf)[4], const AttnUnit& u, bf16* og, float* lse) {
;     ...
;     ATT_VLOAD(0, 0);
; #pragma unroll
;     for (int kk = 0; kk < 5; ++kk) {
;         if (kk < 4) ATT_VLOAD(kk + 1, (kk + 1) & 1);
; #pragma unroll
;         for (int c = 0; c < 8; ++c) {
;             const s16x4 lo = vlo[kk & 1][c], hi = vhi[kk & 1][c];
;             const bf16x8 vf = (bf16x8){lo[0], lo[1], lo[2], lo[3], hi[0], hi[1], hi[2], hi[3]};
;             o[c] = __builtin_amdgcn_mfma_f32_16x16x32_bf16(vf, pf[kk], o[c], 0, 0, 0);
;         }
;     }
	v_mfma_f32_16x16x32_bf16 v[76:79], v[188:191], v[56:59], v[76:79]
	v_bitop3_b32 v133, v133, s77, v85 bitop3:0x36
	v_add_u32_e32 v71, s73, v71
	v_lshlrev_b32_e32 v66, 4, v66
	v_mfma_f32_16x16x32_bf16 v[86:89], v[192:195], v[56:59], v[86:89]
	v_add_u32_e32 v133, s73, v133
	ds_read_b64_tr_b16 v[186:187], v71
	v_bitop3_b32 v66, v66, s77, v85 bitop3:0x36
	v_mfma_f32_16x16x32_bf16 v[134:137], v[196:199], v[56:59], v[134:137]
	ds_read_b64_tr_b16 v[152:153], v133
	v_add_u32_e32 v64, s73, v64
	v_add_u32_e32 v66, s73, v66
	v_mfma_f32_16x16x32_bf16 v[138:141], v[200:203], v[56:59], v[138:141]
	ds_read_b64_tr_b16 v[64:65], v64
	ds_read_b64_tr_b16 v[66:67], v66
	v_mfma_f32_16x16x32_bf16 v[142:145], v[204:207], v[56:59], v[142:145]
	s_waitcnt lgkmcnt(14)
	v_mfma_f32_16x16x32_bf16 v[146:149], v[154:157], v[56:59], v[146:149]
	v_mfma_f32_16x16x32_bf16 v[56:59], v[158:161], v[56:59], v[60:63]
	s_nop 2
	v_or_b32_e32 v60, s78, v111
	v_lshl_or_b32 v71, v60, 8, v114
	v_or_b32_e32 v60, 4, v60
	v_bitop3_b32 v133, v71, s77, v117 bitop3:0x36
	v_bfe_u32 v83, v60, 2, 2
	v_add_u32_e32 v133, s73, v133
	ds_read_b64_tr_b16 v[154:155], v133
	v_bitop3_b32 v133, v83, v116, v113 bitop3:0x36
	v_lshl_or_b32 v85, v60, 8, v114
	v_lshlrev_b32_e32 v133, 4, v133
	v_bitop3_b32 v133, v133, s77, v85 bitop3:0x36
	v_add_u32_e32 v133, s73, v133
	ds_read_b64_tr_b16 v[156:157], v133
	v_bitop3_b32 v133, v71, s77, v119 bitop3:0x36
	v_add_u32_e32 v133, s73, v133
	ds_read_b64_tr_b16 v[158:159], v133
	v_bitop3_b32 v133, v83, v118, v113 bitop3:0x36
	v_lshlrev_b32_e32 v133, 4, v133
	v_bitop3_b32 v133, v133, s77, v85 bitop3:0x36
	v_add_u32_e32 v133, s73, v133
	s_waitcnt lgkmcnt(3)
	v_mfma_f32_16x16x32_bf16 v[64:67], v[64:67], v[52:55], v[72:75]
	ds_read_b64_tr_b16 v[160:161], v133
	v_bitop3_b32 v62, v83, v112, v113 bitop3:0x36
	v_lshlrev_b32_e32 v62, 4, v62
	v_bitop3_b32 v72, v71, s77, v121 bitop3:0x36
	v_add_u32_e32 v133, s73, v72
	v_mfma_f32_16x16x32_bf16 v[72:75], v[162:165], v[52:55], v[76:79]
	v_bitop3_b32 v60, v71, s77, v115 bitop3:0x36
	v_bitop3_b32 v62, v62, s77, v85 bitop3:0x36
	v_add_u32_e32 v60, s73, v60
	ds_read_b64_tr_b16 v[76:77], v133
	v_bitop3_b32 v133, v71, s77, v123 bitop3:0x36
	v_add_u32_e32 v133, s73, v133
	ds_read_b64_tr_b16 v[162:163], v133
	v_bitop3_b32 v133, v83, v122, v113 bitop3:0x36
	v_lshlrev_b32_e32 v133, 4, v133
	v_bitop3_b32 v133, v133, s77, v85 bitop3:0x36
	v_add_u32_e32 v133, s73, v133
	v_add_u32_e32 v62, s73, v62
	ds_read_b64_tr_b16 v[164:165], v133
	v_bitop3_b32 v133, v71, s77, v126 bitop3:0x36
	ds_read_b64_tr_b16 v[60:61], v60
	ds_read_b64_tr_b16 v[62:63], v62
	v_add_u32_e32 v133, s73, v133
	v_mfma_f32_16x16x32_bf16 v[146:149], v[150:153], v[52:55], v[146:149]
	ds_read_b64_tr_b16 v[150:151], v133
	v_bitop3_b32 v133, v83, v124, v113 bitop3:0x36
	v_bitop3_b32 v78, v83, v120, v113 bitop3:0x36
	v_mfma_f32_16x16x32_bf16 v[86:89], v[166:169], v[52:55], v[86:89]
	v_lshlrev_b32_e32 v78, 4, v78
	v_bitop3_b32 v78, v78, s77, v85 bitop3:0x36
	v_add_u32_e32 v78, s73, v78
	v_mfma_f32_16x16x32_bf16 v[134:137], v[170:173], v[52:55], v[134:137]
	ds_read_b64_tr_b16 v[78:79], v78
	v_mfma_f32_16x16x32_bf16 v[138:141], v[174:177], v[52:55], v[138:141]
	v_mfma_f32_16x16x32_bf16 v[142:145], v[180:183], v[52:55], v[142:145]
	v_mfma_f32_16x16x32_bf16 v[56:59], v[184:187], v[52:55], v[56:59]
	v_lshlrev_b32_e32 v52, 4, v133
	v_bitop3_b32 v52, v52, s77, v85 bitop3:0x36
	v_bitop3_b32 v54, v83, v127, v113 bitop3:0x36
	v_add_u32_e32 v52, s73, v52
	v_lshlrev_b32_e32 v54, 4, v54
	ds_read_b64_tr_b16 v[152:153], v52
	v_bitop3_b32 v52, v71, s77, v128 bitop3:0x36
	v_bitop3_b32 v54, v54, s77, v85 bitop3:0x36
	v_add_u32_e32 v52, s73, v52
	v_add_u32_e32 v54, s73, v54
	ds_read_b64_tr_b16 v[52:53], v52
	ds_read_b64_tr_b16 v[54:55], v54
	v_bitop3_b32 v71, v71, s77, v130 bitop3:0x36
	v_add_u32_e32 v71, s73, v71
	s_waitcnt lgkmcnt(5)
; __device__ __forceinline__ unsigned cvtpk(float lo, float hi) { f32x2_t v = {lo, hi}; bf16x2_t b = __builtin_convertvector(v, bf16x2_t); return __builtin_bit_cast(unsigned, b); }
; __device__ __forceinline__ void attn_compute(LAS unsigned char* lds, const bf16x8 (&qf)[4], const AttnUnit& u, bf16* og, float* lse) {
;     ...
;             o[c] = __builtin_amdgcn_mfma_f32_16x16x32_bf16(vf, pf[kk], o[c], 0, 0, 0);
;         }
;     }
;     ...
;     const float rl = 1.0f / l;
;     bf16* op = og + qtok * 1024 + h * 128 + 4 * kg;
; #pragma unroll
;     for (int c = 0; c < 8; ++c) { v2u wv; wv.x = cvtpk(o[c][0] * rl, o[c][1] * rl); wv.y = cvtpk(o[c][2] * rl, o[c][3] * rl); *(v2u*)(op + 16 * c) = wv; }
;     if (kg == 0) lse[qtok * 8 + h] = mx + __builtin_amdgcn_logf(l);
	v_mfma_f32_16x16x32_bf16 v[60:63], v[60:63], v[48:51], v[64:67]
	v_mfma_f32_16x16x32_bf16 v[64:67], v[154:157], v[48:51], v[72:75]
	v_mfma_f32_16x16x32_bf16 v[72:75], v[158:161], v[48:51], v[86:89]
	s_nop 2
	ds_read_b64_tr_b16 v[86:87], v71
	v_bitop3_b32 v71, v83, v129, v113 bitop3:0x36
	v_lshlrev_b32_e32 v71, 4, v71
	v_bitop3_b32 v71, v71, s77, v85 bitop3:0x36
	v_add_u32_e32 v71, s73, v71
	ds_read_b64_tr_b16 v[88:89], v71
	s_waitcnt lgkmcnt(5)
	v_mfma_f32_16x16x32_bf16 v[76:79], v[76:79], v[48:51], v[134:137]
	v_mov_b32_e32 v85, v81
	v_mfma_f32_16x16x32_bf16 v[134:137], v[162:165], v[48:51], v[138:141]
	s_waitcnt lgkmcnt(4)
	v_mfma_f32_16x16x32_bf16 v[138:141], v[150:153], v[48:51], v[142:145]
	v_lshlrev_b64 v[150:151], s8, v[80:81]
	s_lshl_b32 s8, s76, 8
	s_waitcnt lgkmcnt(2)
	v_mfma_f32_16x16x32_bf16 v[142:145], v[52:55], v[48:51], v[146:149]
	v_add_f32_e32 v54, v69, v70
	v_div_scale_f32 v55, s[30:31], v54, v54, 1.0
	v_rcp_f32_e32 v69, v55
	s_waitcnt lgkmcnt(0)
	v_mfma_f32_16x16x32_bf16 v[48:51], v[86:89], v[48:51], v[56:59]
	v_lshl_add_u64 v[52:53], s[62:63], 0, v[150:151]
	s_nop 1
	v_fma_f32 v56, -v55, v69, 1.0
	v_fmac_f32_e32 v69, v56, v69
	v_div_scale_f32 v56, vcc, 1.0, v54, 1.0
	v_mul_f32_e32 v57, v56, v69
	v_fma_f32 v58, -v55, v57, v56
	v_fmac_f32_e32 v57, v58, v69
	v_fma_f32 v55, -v55, v57, v56
	v_div_fmas_f32 v55, v55, v69, v57
	v_lshlrev_b64 v[58:59], 11, v[52:53]
	v_div_fixup_f32 v56, v55, v54, 1.0
	v_lshl_add_u64 v[58:59], s[60:61], 0, v[58:59]
	v_lshl_add_u64 v[58:59], v[58:59], 0, s[8:9]
	v_pk_mul_f32 v[60:61], v[56:57], v[60:61] op_sel_hi:[0,1]
	v_pk_mul_f32 v[62:63], v[56:57], v[62:63] op_sel_hi:[0,1]
	v_lshl_add_u64 v[58:59], v[58:59], 0, v[84:85]
	v_cvt_pk_bf16_f32 v60, v60, v61
	v_cvt_pk_bf16_f32 v61, v62, v63
	global_store_dwordx2 v[58:59], v[60:61], off
	v_pk_mul_f32 v[60:61], v[56:57], v[64:65] op_sel_hi:[0,1]
	v_pk_mul_f32 v[62:63], v[56:57], v[66:67] op_sel_hi:[0,1]
	v_cvt_pk_bf16_f32 v60, v60, v61
	v_cvt_pk_bf16_f32 v61, v62, v63
	global_store_dwordx2 v[58:59], v[60:61], off offset:32
	v_pk_mul_f32 v[60:61], v[56:57], v[72:73] op_sel_hi:[0,1]
	v_pk_mul_f32 v[62:63], v[56:57], v[74:75] op_sel_hi:[0,1]
	v_cvt_pk_bf16_f32 v60, v60, v61
	v_cvt_pk_bf16_f32 v61, v62, v63
	global_store_dwordx2 v[58:59], v[60:61], off offset:64
	v_pk_mul_f32 v[60:61], v[56:57], v[76:77] op_sel_hi:[0,1]
	v_pk_mul_f32 v[62:63], v[56:57], v[78:79] op_sel_hi:[0,1]
	v_cvt_pk_bf16_f32 v60, v60, v61
	v_cvt_pk_bf16_f32 v61, v62, v63
	global_store_dwordx2 v[58:59], v[60:61], off offset:96
	v_pk_mul_f32 v[60:61], v[56:57], v[134:135] op_sel_hi:[0,1]
	v_pk_mul_f32 v[62:63], v[56:57], v[136:137] op_sel_hi:[0,1]
	v_cvt_pk_bf16_f32 v60, v60, v61
	v_cvt_pk_bf16_f32 v61, v62, v63
	global_store_dwordx2 v[58:59], v[60:61], off offset:128
	v_pk_mul_f32 v[60:61], v[56:57], v[138:139] op_sel_hi:[0,1]
	v_pk_mul_f32 v[62:63], v[56:57], v[140:141] op_sel_hi:[0,1]
	v_cvt_pk_bf16_f32 v60, v60, v61
	v_cvt_pk_bf16_f32 v61, v62, v63
	global_store_dwordx2 v[58:59], v[60:61], off offset:160
	v_pk_mul_f32 v[60:61], v[56:57], v[142:143] op_sel_hi:[0,1]
	v_pk_mul_f32 v[62:63], v[56:57], v[144:145] op_sel_hi:[0,1]
	v_pk_mul_f32 v[48:49], v[56:57], v[48:49] op_sel_hi:[0,1]
	v_pk_mul_f32 v[50:51], v[56:57], v[50:51] op_sel_hi:[0,1]
	v_cvt_pk_bf16_f32 v60, v60, v61
	v_cvt_pk_bf16_f32 v61, v62, v63
	v_cvt_pk_bf16_f32 v48, v48, v49
	v_cvt_pk_bf16_f32 v49, v50, v51
	global_store_dwordx2 v[58:59], v[60:61], off offset:192
	global_store_dwordx2 v[58:59], v[48:49], off offset:224
	s_and_saveexec_b64 s[60:61], s[6:7]
	s_cbranch_execz .LBB0_146
	v_log_f32_e32 v48, v54
	s_add_i32 s30, s75, -1
	s_lshr_b32 s31, s30, 8
	s_mul_hi_u32 s31, s31, 0x55555556
	s_and_b32 s30, s30, 0xff
	s_lshl_b32 s31, s31, 8
	s_add_i32 s30, s30, s31
	s_lshl_b32 s30, s30, 9
	s_lshl_b32 s31, s10, 20
	s_add_i32 s30, s30, s31
	s_add_u32 s10, s0, s30
	s_addc_u32 s11, s1, 0
	v_add_f32_e32 v50, v68, v48
	v_lshrrev_b32_e32 v48, 6, v178
	v_and_b32_e32 v49, 15, v178
	v_lshl_or_b32 v48, v48, 4, v49
	v_lshlrev_b32_e32 v48, 2, v48
	global_store_dword v48, v50, s[10:11]
	s_branch .LBB0_146

; __global__ void __launch_bounds__(NTHREADS, 2) fwd_megakernel(Args args) {
;     ...
;         for (size_t it = gt; it < nitems; it += NGT) {
;             const size_t tok0 = (it >> 7) * TB; const int ac = (int)(it & 127), h = ac >> 4, c0 = ac * 8;
; #pragma unroll 4
;             for (int t = 0; t < TB; ++t) {
;                 const size_t tok = tok0 + t;
;                 const float l0 = LSE[tok * 8 + h], l1 = LSE[(size_t)MTOK * 8 + tok * 8 + h], l2 = LSE[(size_t)2 * MTOK * 8 + tok * 8 + h];
;                 const float mm = fmaxf(l0, fmaxf(l1, l2));
;                 float w0 = __builtin_amdgcn_exp2f(l0 - mm), w1 = __builtin_amdgcn_exp2f(l1 - mm), w2 = __builtin_amdgcn_exp2f(l2 - mm);
;                 const float inv = 1.0f / (w0 + w1 + w2); w0 *= inv; w1 *= inv; w2 *= inv;
;                 const v4u a0 = *(const v4u*)(OG0 + tok * 1024 + c0), a1 = *(const v4u*)(OG1 + tok * 1024 + c0), a2 = *(const v4u*)(OG2 + tok * 1024 + c0);
.LBB0_206:
	s_or_b64 exec, exec, s[4:5]
	v_mov_b32_e32 v2, v178
	v_readlane_b32 s0, v244, 2
	s_waitcnt lgkmcnt(0)
	s_barrier
	v_readlane_b32 s1, v244, 3
	v_ashrrev_i32_e32 v3, 31, v2
	s_nop 0
	v_lshl_add_u64 v[0:1], s[0:1], 0, v[2:3]
	s_mov_b64 s[0:1], 0x20000
	v_cmp_gt_u64_e32 vcc, s[0:1], v[0:1]
	s_and_saveexec_b64 s[6:7], vcc
	s_cbranch_execz .LBB0_211
	s_add_u32 s68, s40, 0x3fc00000
	s_addc_u32 s69, s41, 0
	s_mov_b32 s71, 0xffffd004
	v_and_b32_e32 v6, 0x70, v2
	v_and_b32_e32 v4, 0x7f, v2
	v_mov_b32_e32 v5, 0
	v_lshlrev_b32_e32 v4, 4, v4
	v_lshrrev_b32_e32 v6, 2, v6
	v_mov_b32_e32 v7, v5
	s_mov_b64 s[8:9], 0
	s_mov_b32 s0, 0x7fe0000
	s_mov_b32 s1, 0x3ff0000
	s_mov_b32 s29, 0xffc00
	s_mov_b32 s33, 0x7c00000
	s_mov_b32 s46, 0xbc00000
	s_brev_b32 s47, 16
	s_movk_i32 s62, 0x1000
	s_mov_b32 s63, 0x7c01000
	s_mov_b32 s64, 0xbc01000
	s_mov_b32 s65, 0x8001000
	s_movk_i32 s66, 0x2000
	s_mov_b64 s[10:11], 0x4000
	s_mov_b64 s[56:57], 0x2000
	s_mov_b64 s[58:59], 0x80
	s_mov_b64 s[60:61], 0x1ffff
	v_mov_b64_e32 v[8:9], v[0:1]
.LBB0_208:
	v_lshlrev_b32_e32 v10, 10, v8
	v_lshlrev_b32_e32 v12, 9, v8
	v_lshlrev_b32_e32 v14, 3, v8
	v_and_or_b32 v10, v10, s0, v4
	v_mov_b32_e32 v11, v5
	v_and_or_b32 v12, v12, s1, v4
	v_mov_b32_e32 v13, v5
	v_and_or_b32 v14, v14, s29, v6
	v_mov_b32_e32 v15, v7
	v_and_b32_e32 v88, 0x1c000, v8
	v_lshlrev_b32_e32 v88, 3, v88
	v_and_b32_e32 v89, 0x70, v8
	v_lshl_or_b32 v88, v89, 10, v88
	v_and_b32_e32 v89, 0x3f80, v8
	v_or_b32_e32 v84, v88, v89
	v_lshrrev_b32_e32 v85, 2, v89
	v_add_u32_e32 v85, v85, v88
	v_add_u32_e32 v86, 0x103000, v85
	v_add_u32_e32 v85, 0x101000, v85
	v_lshrrev_b32_e32 v87, 4, v89
	v_add_u32_e32 v87, v87, v88
	v_add_u32_e32 v87, 0x200000, v87
	s_mov_b32 s67, 32
.LBB0_209:
	v_lshl_add_u64 v[20:21], s[40:41], 0, v[12:13]
	v_add_co_u32_e64 v28, s[4:5], s33, v20
	v_lshl_add_u64 v[26:27], s[40:41], 0, v[14:15]
	s_nop 0
	v_addc_co_u32_e64 v29, s[4:5], 0, v21, s[4:5]
	v_add_co_u32_e64 v18, s[4:5], s63, v20
	v_lshl_add_u64 v[22:23], s[38:39], 0, v[12:13]
	s_nop 0
	v_addc_co_u32_e64 v19, s[4:5], 0, v21, s[4:5]
	v_add_co_u32_e64 v30, s[4:5], s46, v20
	v_add_co_u32_e32 v24, vcc, 0x3fc00000, v26
	s_nop 0
	v_addc_co_u32_e64 v31, s[4:5], 0, v21, s[4:5]
	v_add_co_u32_e64 v20, s[4:5], s64, v20
	v_addc_co_u32_e32 v25, vcc, 0, v27, vcc
	s_nop 0
	v_addc_co_u32_e64 v21, s[4:5], 0, v21, s[4:5]
	v_add_co_u32_e64 v32, s[4:5], s47, v22
	v_add_co_u32_e32 v50, vcc, 0x3fd00000, v26
	s_nop 0
	v_addc_co_u32_e64 v33, s[4:5], 0, v23, s[4:5]
	v_add_co_u32_e64 v22, s[4:5], s65, v22
	v_addc_co_u32_e32 v51, vcc, 0, v27, vcc
	s_nop 0
	v_addc_co_u32_e64 v23, s[4:5], 0, v23, s[4:5]
	global_load_dwordx4 v[36:39], v[20:21], off offset:-4096
	global_load_dwordx4 v[40:43], v[22:23], off offset:-4096
	global_load_dword v68, v84, s[68:69]
	v_add_co_u32_e32 v52, vcc, 0x3fe00000, v26
	v_lshl_add_u64 v[16:17], s[38:39], 0, v[10:11]
	s_nop 0
	v_addc_co_u32_e32 v53, vcc, 0, v27, vcc
	global_load_dword v69, v85, s[68:69] offset:-4096
	global_load_dword v70, v87, s[68:69]
	global_load_dwordx4 v[44:47], v[18:19], off offset:-4096
	v_add_co_u32_e64 v82, s[4:5], s62, v16
	s_add_i32 s67, s67, -4
	s_cmp_eq_u32 s67, 16
	s_cselect_b32 s70, s71, 0x1000
	s_nop 0
	v_addc_co_u32_e64 v83, s[4:5], 0, v17, s[4:5]
	v_add_co_u32_e64 v48, s[4:5], s66, v16
	v_lshl_add_u64 v[10:11], v[10:11], 0, s[10:11]
	s_nop 0
	v_addc_co_u32_e64 v49, s[4:5], 0, v17, s[4:5]
	v_lshl_add_u64 v[12:13], v[12:13], 0, s[56:57]
	v_lshl_add_u64 v[14:15], v[14:15], 0, s[58:59]
	s_cmp_eq_u32 s67, 0
	s_waitcnt vmcnt(5)
	v_lshlrev_b32_e32 v26, 16, v36
	v_and_b32_e32 v55, 0xffff0000, v36
	v_lshlrev_b32_e32 v36, 16, v37
	v_and_b32_e32 v59, 0xffff0000, v37
	v_lshlrev_b32_e32 v60, 16, v38
	v_and_b32_e32 v63, 0xffff0000, v38
	v_lshlrev_b32_e32 v38, 16, v39
	s_waitcnt vmcnt(1)
	v_max3_f32 v71, v68, v69, v70
	s_waitcnt vmcnt(0)
	v_and_b32_e32 v27, 0xffff0000, v44
	v_lshlrev_b32_e32 v54, 16, v44
	v_and_b32_e32 v61, 0xffff0000, v46
	v_lshlrev_b32_e32 v62, 16, v46
	v_sub_f32_e32 v44, v68, v71
	v_sub_f32_e32 v46, v69, v71
	v_and_b32_e32 v67, 0xffff0000, v39
	v_and_b32_e32 v37, 0xffff0000, v45
	v_lshlrev_b32_e32 v58, 16, v45
	v_and_b32_e32 v39, 0xffff0000, v47
	v_lshlrev_b32_e32 v66, 16, v47
	v_sub_f32_e32 v47, v70, v71
	v_exp_f32_e32 v45, v44
	v_exp_f32_e32 v44, v46
	v_exp_f32_e32 v47, v47
	v_lshlrev_b32_e32 v56, 16, v40
	v_and_b32_e32 v57, 0xffff0000, v40
	v_add_f32_e32 v46, v45, v44
	v_add_f32_e32 v46, v47, v46
	v_div_scale_f32 v68, s[4:5], v46, v46, 1.0
	v_rcp_f32_e32 v70, v68
	v_div_scale_f32 v69, vcc, 1.0, v46, 1.0
	v_lshlrev_b32_e32 v40, 16, v41
	v_fma_f32 v71, -v68, v70, 1.0
	v_fmac_f32_e32 v70, v71, v70
	v_mul_f32_e32 v71, v69, v70
	v_fma_f32 v72, -v68, v71, v69
	v_fmac_f32_e32 v71, v72, v70
	v_fma_f32 v68, -v68, v71, v69
	v_div_fmas_f32 v68, v68, v70, v71
	v_div_fixup_f32 v46, v68, v46, 1.0
	v_pk_mul_f32 v[44:45], v[44:45], v[46:47] op_sel_hi:[1,0]
	v_mul_f32_e32 v68, v47, v46
	v_pk_mul_f32 v[46:47], v[44:45], v[54:55] op_sel:[1,0] op_sel_hi:[0,1]
	v_pk_mul_f32 v[54:55], v[44:45], v[58:59] op_sel:[1,0] op_sel_hi:[0,1]
	v_pk_mul_f32 v[58:59], v[44:45], v[62:63] op_sel:[1,0] op_sel_hi:[0,1]
	v_pk_mul_f32 v[62:63], v[44:45], v[66:67] op_sel:[1,0] op_sel_hi:[0,1]
	v_and_b32_e32 v41, 0xffff0000, v41
	v_lshlrev_b32_e32 v64, 16, v42
	v_and_b32_e32 v65, 0xffff0000, v42
	v_lshlrev_b32_e32 v42, 16, v43
	v_and_b32_e32 v43, 0xffff0000, v43
	v_pk_fma_f32 v[26:27], v[44:45], v[26:27], v[46:47]
	v_pk_fma_f32 v[36:37], v[44:45], v[36:37], v[54:55]
	v_pk_fma_f32 v[46:47], v[44:45], v[60:61], v[58:59]
	v_pk_fma_f32 v[38:39], v[44:45], v[38:39], v[62:63]
	v_pk_fma_f32 v[26:27], v[68:69], v[56:57], v[26:27] op_sel_hi:[0,1,1]
	v_pk_fma_f32 v[40:41], v[68:69], v[40:41], v[36:37] op_sel_hi:[0,1,1]
	v_pk_fma_f32 v[44:45], v[68:69], v[64:65], v[46:47] op_sel_hi:[0,1,1]
	v_pk_fma_f32 v[42:43], v[68:69], v[42:43], v[38:39] op_sel_hi:[0,1,1]
	v_cvt_pk_bf16_f32 v74, v26, v27
	v_cvt_pk_bf16_f32 v75, v40, v41
	v_cvt_pk_bf16_f32 v76, v44, v45
	v_cvt_pk_bf16_f32 v77, v42, v43
	global_load_dword v60, v84, s[68:69] offset:4
	global_load_dword v61, v85, s[68:69]
	global_load_dword v62, v87, s[68:69] offset:1024
	s_nop 0
	global_load_dwordx4 v[36:39], v[30:31], off offset:2048
	s_nop 0
	global_load_dwordx4 v[26:29], v[28:29], off offset:2048
	s_nop 0
	global_load_dwordx4 v[30:33], v[32:33], off offset:2048
	global_store_dwordx4 v[16:17], v[74:77], off offset:2048
	s_waitcnt vmcnt(4)
; __device__ __forceinline__ unsigned cvtpk(float lo, float hi) { f32x2_t v = {lo, hi}; bf16x2_t b = __builtin_convertvector(v, bf16x2_t); return __builtin_bit_cast(unsigned, b); }
; __global__ void __launch_bounds__(NTHREADS, 2) fwd_megakernel(Args args) {
;     ...
;                 const size_t tok = tok0 + t;
;                 const float l0 = LSE[tok * 8 + h], l1 = LSE[(size_t)MTOK * 8 + tok * 8 + h], l2 = LSE[(size_t)2 * MTOK * 8 + tok * 8 + h];
;                 const float mm = fmaxf(l0, fmaxf(l1, l2));
;                 float w0 = __builtin_amdgcn_exp2f(l0 - mm), w1 = __builtin_amdgcn_exp2f(l1 - mm), w2 = __builtin_amdgcn_exp2f(l2 - mm);
;                 const float inv = 1.0f / (w0 + w1 + w2); w0 *= inv; w1 *= inv; w2 *= inv;
;                 const v4u a0 = *(const v4u*)(OG0 + tok * 1024 + c0), a1 = *(const v4u*)(OG1 + tok * 1024 + c0), a2 = *(const v4u*)(OG2 + tok * 1024 + c0);
;                 v4u o;
;                 o.x = cvtpk(w0 * bflo(a0.x) + w1 * bflo(a1.x) + w2 * bflo(a2.x), w0 * bfhi(a0.x) + w1 * bfhi(a1.x) + w2 * bfhi(a2.x));
;                 o.y = cvtpk(w0 * bflo(a0.y) + w1 * bflo(a1.y) + w2 * bflo(a2.y), w0 * bfhi(a0.y) + w1 * bfhi(a1.y) + w2 * bfhi(a2.y));
;                 o.z = cvtpk(w0 * bflo(a0.z) + w1 * bflo(a1.z) + w2 * bflo(a2.z), w0 * bfhi(a0.z) + w1 * bfhi(a1.z) + w2 * bfhi(a2.z));
;                 o.w = cvtpk(w0 * bflo(a0.w) + w1 * bflo(a1.w) + w2 * bflo(a2.w), w0 * bfhi(a0.w) + w1 * bfhi(a1.w) + w2 * bfhi(a2.w));
;                 *(v4u*)(YMIX + tok * DM + CONVW + c0) = o;
	v_max3_f32 v63, v60, v61, v62
	s_waitcnt vmcnt(3)
	v_lshlrev_b32_e32 v40, 16, v36
	v_and_b32_e32 v43, 0xffff0000, v36
	v_lshlrev_b32_e32 v36, 16, v38
	v_and_b32_e32 v55, 0xffff0000, v38
	v_sub_f32_e32 v38, v60, v63
	v_sub_f32_e32 v60, v61, v63
	s_waitcnt vmcnt(2)
	v_and_b32_e32 v41, 0xffff0000, v26
	v_lshlrev_b32_e32 v42, 16, v26
	v_lshlrev_b32_e32 v46, 16, v37
	v_and_b32_e32 v47, 0xffff0000, v27
	v_lshlrev_b32_e32 v26, 16, v27
	v_and_b32_e32 v27, 0xffff0000, v37
	v_and_b32_e32 v37, 0xffff0000, v28
	v_lshlrev_b32_e32 v54, 16, v28
	v_lshlrev_b32_e32 v58, 16, v39
	v_and_b32_e32 v59, 0xffff0000, v29
	v_lshlrev_b32_e32 v28, 16, v29
	v_and_b32_e32 v29, 0xffff0000, v39
	v_sub_f32_e32 v61, v62, v63
	v_exp_f32_e32 v39, v38
	v_exp_f32_e32 v38, v60
	v_exp_f32_e32 v61, v61
	s_waitcnt vmcnt(1)
	v_lshlrev_b32_e32 v44, 16, v30
	v_and_b32_e32 v45, 0xffff0000, v30
	v_add_f32_e32 v60, v39, v38
	v_add_f32_e32 v60, v61, v60
	v_div_scale_f32 v62, s[4:5], v60, v60, 1.0
	v_rcp_f32_e32 v64, v62
	v_div_scale_f32 v63, vcc, 1.0, v60, 1.0
	v_lshlrev_b32_e32 v30, 16, v31
	v_fma_f32 v65, -v62, v64, 1.0
	v_fmac_f32_e32 v64, v65, v64
	v_mul_f32_e32 v65, v63, v64
	v_fma_f32 v66, -v62, v65, v63
	v_fmac_f32_e32 v65, v66, v64
	v_fma_f32 v62, -v62, v65, v63
	v_div_fmas_f32 v62, v62, v64, v65
	v_div_fixup_f32 v60, v62, v60, 1.0
	v_pk_mul_f32 v[38:39], v[38:39], v[60:61] op_sel_hi:[1,0]
	v_and_b32_e32 v31, 0xffff0000, v31
	v_pk_mul_f32 v[42:43], v[38:39], v[42:43] op_sel:[1,0] op_sel_hi:[0,1]
	v_pk_mul_f32 v[26:27], v[38:39], v[26:27] op_sel:[1,0] op_sel_hi:[0,1]
	v_pk_mul_f32 v[54:55], v[38:39], v[54:55] op_sel:[1,0] op_sel_hi:[0,1]
	v_pk_mul_f32 v[28:29], v[38:39], v[28:29] op_sel:[1,0] op_sel_hi:[0,1]
	v_lshlrev_b32_e32 v56, 16, v32
	v_and_b32_e32 v57, 0xffff0000, v32
	v_lshlrev_b32_e32 v32, 16, v33
	v_and_b32_e32 v33, 0xffff0000, v33
	v_mul_f32_e32 v62, v61, v60
	v_pk_fma_f32 v[40:41], v[38:39], v[40:41], v[42:43]
	v_pk_fma_f32 v[26:27], v[38:39], v[46:47], v[26:27]
	v_pk_fma_f32 v[36:37], v[38:39], v[36:37], v[54:55]
	v_pk_fma_f32 v[28:29], v[38:39], v[58:59], v[28:29]
	v_pk_fma_f32 v[38:39], v[62:63], v[44:45], v[40:41] op_sel_hi:[0,1,1]
	v_pk_fma_f32 v[30:31], v[62:63], v[30:31], v[26:27] op_sel_hi:[0,1,1]
	v_pk_fma_f32 v[36:37], v[62:63], v[56:57], v[36:37] op_sel_hi:[0,1,1]
	v_pk_fma_f32 v[32:33], v[62:63], v[32:33], v[28:29] op_sel_hi:[0,1,1]
	v_cvt_pk_bf16_f32 v78, v38, v39
	v_cvt_pk_bf16_f32 v79, v30, v31
	v_cvt_pk_bf16_f32 v80, v36, v37
	v_cvt_pk_bf16_f32 v81, v32, v33
	global_load_dword v58, v84, s[68:69] offset:8
	global_load_dword v59, v86, s[68:69] offset:-4096
	global_load_dword v60, v87, s[68:69] offset:2048
	s_nop 0
	global_load_dwordx4 v[26:29], v[20:21], off
	global_load_dwordx4 v[30:33], v[18:19], off
	global_load_dwordx4 v[34:37], v[22:23], off
	global_store_dwordx4 v[82:83], v[78:81], off offset:2048
	s_waitcnt vmcnt(4)
	v_max3_f32 v61, v58, v59, v60
	s_waitcnt vmcnt(3)
	v_lshlrev_b32_e32 v38, 16, v26
	s_waitcnt vmcnt(2)
	v_and_b32_e32 v39, 0xffff0000, v30
	s_waitcnt vmcnt(1)
; __device__ __forceinline__ unsigned cvtpk(float lo, float hi) { f32x2_t v = {lo, hi}; bf16x2_t b = __builtin_convertvector(v, bf16x2_t); return __builtin_bit_cast(unsigned, b); }
; __global__ void __launch_bounds__(NTHREADS, 2) fwd_megakernel(Args args) {
;     ...
;                 const size_t tok = tok0 + t;
;                 const float l0 = LSE[tok * 8 + h], l1 = LSE[(size_t)MTOK * 8 + tok * 8 + h], l2 = LSE[(size_t)2 * MTOK * 8 + tok * 8 + h];
;                 const float mm = fmaxf(l0, fmaxf(l1, l2));
;                 float w0 = __builtin_amdgcn_exp2f(l0 - mm), w1 = __builtin_amdgcn_exp2f(l1 - mm), w2 = __builtin_amdgcn_exp2f(l2 - mm);
;                 const float inv = 1.0f / (w0 + w1 + w2); w0 *= inv; w1 *= inv; w2 *= inv;
;                 const v4u a0 = *(const v4u*)(OG0 + tok * 1024 + c0), a1 = *(const v4u*)(OG1 + tok * 1024 + c0), a2 = *(const v4u*)(OG2 + tok * 1024 + c0);
;                 v4u o;
;                 o.x = cvtpk(w0 * bflo(a0.x) + w1 * bflo(a1.x) + w2 * bflo(a2.x), w0 * bfhi(a0.x) + w1 * bfhi(a1.x) + w2 * bfhi(a2.x));
;                 o.y = cvtpk(w0 * bflo(a0.y) + w1 * bflo(a1.y) + w2 * bflo(a2.y), w0 * bfhi(a0.y) + w1 * bfhi(a1.y) + w2 * bfhi(a2.y));
;                 o.z = cvtpk(w0 * bflo(a0.z) + w1 * bflo(a1.z) + w2 * bflo(a2.z), w0 * bfhi(a0.z) + w1 * bfhi(a1.z) + w2 * bfhi(a2.z));
;                 o.w = cvtpk(w0 * bflo(a0.w) + w1 * bflo(a1.w) + w2 * bflo(a2.w), w0 * bfhi(a0.w) + w1 * bfhi(a1.w) + w2 * bfhi(a2.w));
;                 *(v4u*)(YMIX + tok * DM + CONVW + c0) = o;
	v_lshlrev_b32_e32 v54, 16, v36
	v_and_b32_e32 v55, 0xffff0000, v36
	v_sub_f32_e32 v36, v58, v61
	v_sub_f32_e32 v58, v59, v61
	v_lshlrev_b32_e32 v40, 16, v30
	v_and_b32_e32 v41, 0xffff0000, v26
	v_lshlrev_b32_e32 v42, 16, v34
	v_and_b32_e32 v43, 0xffff0000, v34
	v_and_b32_e32 v45, 0xffff0000, v31
	v_lshlrev_b32_e32 v26, 16, v31
	v_lshlrev_b32_e32 v30, 16, v35
	v_and_b32_e32 v31, 0xffff0000, v35
	v_lshlrev_b32_e32 v34, 16, v28
	v_and_b32_e32 v35, 0xffff0000, v32
	v_lshlrev_b32_e32 v46, 16, v32
	v_and_b32_e32 v47, 0xffff0000, v28
	v_and_b32_e32 v57, 0xffff0000, v33
	v_lshlrev_b32_e32 v28, 16, v33
	v_lshlrev_b32_e32 v32, 16, v37
	v_and_b32_e32 v33, 0xffff0000, v37
	v_sub_f32_e32 v59, v60, v61
	v_exp_f32_e32 v37, v36
	v_exp_f32_e32 v36, v58
	v_exp_f32_e32 v59, v59
	v_lshlrev_b32_e32 v44, 16, v27
	v_and_b32_e32 v27, 0xffff0000, v27
	v_add_f32_e32 v58, v37, v36
	v_add_f32_e32 v58, v59, v58
	v_div_scale_f32 v60, s[4:5], v58, v58, 1.0
	v_rcp_f32_e32 v62, v60
	v_div_scale_f32 v61, vcc, 1.0, v58, 1.0
	v_lshlrev_b32_e32 v56, 16, v29
	v_fma_f32 v63, -v60, v62, 1.0
	v_fmac_f32_e32 v62, v63, v62
	v_mul_f32_e32 v63, v61, v62
	v_fma_f32 v64, -v60, v63, v61
	v_fmac_f32_e32 v63, v64, v62
	v_fma_f32 v60, -v60, v63, v61
	v_div_fmas_f32 v60, v60, v62, v63
	v_div_fixup_f32 v58, v60, v58, 1.0
	v_and_b32_e32 v29, 0xffff0000, v29
	v_pk_mul_f32 v[36:37], v[36:37], v[58:59] op_sel_hi:[1,0]
	v_mul_f32_e32 v60, v59, v58
	v_pk_mul_f32 v[40:41], v[36:37], v[40:41] op_sel:[1,0] op_sel_hi:[0,1]
	v_pk_mul_f32 v[26:27], v[36:37], v[26:27] op_sel:[1,0] op_sel_hi:[0,1]
	v_pk_mul_f32 v[46:47], v[36:37], v[46:47] op_sel:[1,0] op_sel_hi:[0,1]
	v_pk_mul_f32 v[28:29], v[36:37], v[28:29] op_sel:[1,0] op_sel_hi:[0,1]
	v_pk_fma_f32 v[38:39], v[36:37], v[38:39], v[40:41]
	v_pk_fma_f32 v[26:27], v[36:37], v[44:45], v[26:27]
	v_pk_fma_f32 v[34:35], v[36:37], v[34:35], v[46:47]
	v_pk_fma_f32 v[28:29], v[36:37], v[56:57], v[28:29]
	v_pk_fma_f32 v[36:37], v[60:61], v[42:43], v[38:39] op_sel_hi:[0,1,1]
	v_pk_fma_f32 v[30:31], v[60:61], v[30:31], v[26:27] op_sel_hi:[0,1,1]
	v_pk_fma_f32 v[34:35], v[60:61], v[54:55], v[34:35] op_sel_hi:[0,1,1]
	v_pk_fma_f32 v[32:33], v[60:61], v[32:33], v[28:29] op_sel_hi:[0,1,1]
	v_cvt_pk_bf16_f32 v74, v36, v37
	v_cvt_pk_bf16_f32 v75, v30, v31
	v_cvt_pk_bf16_f32 v76, v34, v35
	v_cvt_pk_bf16_f32 v77, v32, v33
	global_load_dword v44, v84, s[68:69] offset:12
	global_load_dword v45, v86, s[68:69]
	global_load_dword v46, v87, s[68:69] offset:3072
	s_nop 0
	global_load_dwordx4 v[24:27], v[20:21], off offset:2048
	s_nop 0
	global_load_dwordx4 v[18:21], v[18:19], off offset:2048
	s_nop 0
	global_load_dwordx4 v[28:31], v[22:23], off offset:2048
	global_store_dwordx4 v[48:49], v[74:77], off offset:2048
	s_waitcnt vmcnt(4)
	v_max3_f32 v47, v44, v45, v46
	s_waitcnt vmcnt(3)
	v_lshlrev_b32_e32 v22, 16, v24
	s_waitcnt vmcnt(2)
	v_and_b32_e32 v23, 0xffff0000, v18
	s_waitcnt vmcnt(1)
	v_lshlrev_b32_e32 v40, 16, v30
	v_and_b32_e32 v41, 0xffff0000, v30
	v_sub_f32_e32 v30, v44, v47
	v_sub_f32_e32 v44, v45, v47
	v_lshlrev_b32_e32 v32, 16, v18
	v_and_b32_e32 v33, 0xffff0000, v24
	v_lshlrev_b32_e32 v34, 16, v28
	v_and_b32_e32 v35, 0xffff0000, v28
	v_lshlrev_b32_e32 v36, 16, v25
	v_and_b32_e32 v37, 0xffff0000, v19
	v_lshlrev_b32_e32 v18, 16, v19
	v_and_b32_e32 v19, 0xffff0000, v25
	v_lshlrev_b32_e32 v24, 16, v29
	v_and_b32_e32 v25, 0xffff0000, v29
	v_lshlrev_b32_e32 v28, 16, v26
	v_and_b32_e32 v29, 0xffff0000, v20
	v_lshlrev_b32_e32 v38, 16, v20
	v_and_b32_e32 v39, 0xffff0000, v26
	v_lshlrev_b32_e32 v42, 16, v27
	v_and_b32_e32 v43, 0xffff0000, v21
	v_lshlrev_b32_e32 v20, 16, v21
	v_and_b32_e32 v21, 0xffff0000, v27
	v_lshlrev_b32_e32 v26, 16, v31
	v_and_b32_e32 v27, 0xffff0000, v31
	v_sub_f32_e32 v45, v46, v47
	v_exp_f32_e32 v31, v30
	v_exp_f32_e32 v30, v44
	v_exp_f32_e32 v46, v45
	v_add_f32_e32 v44, v31, v30
	v_add_f32_e32 v45, v46, v44
	v_div_scale_f32 v44, s[4:5], v45, v45, 1.0
	v_rcp_f32_e32 v48, v44
	v_div_scale_f32 v47, vcc, 1.0, v45, 1.0
	v_fma_f32 v49, -v44, v48, 1.0
	v_fmac_f32_e32 v48, v49, v48
	v_mul_f32_e32 v49, v47, v48
	v_fma_f32 v50, -v44, v49, v47
	v_fmac_f32_e32 v49, v50, v48
	v_fma_f32 v44, -v44, v49, v47
	v_div_fmas_f32 v47, v44, v48, v49
	v_add_co_u32_e32 v44, vcc, 0x3000, v16
	v_div_fixup_f32 v16, v47, v45, 1.0
	s_nop 0
	v_addc_co_u32_e32 v45, vcc, 0, v17, vcc
	v_mul_f32_e32 v46, v46, v16
	v_pk_mul_f32 v[16:17], v[30:31], v[16:17] op_sel_hi:[1,0]
	s_nop 0
	v_pk_mul_f32 v[30:31], v[16:17], v[32:33] op_sel:[1,0] op_sel_hi:[0,1]
	v_pk_mul_f32 v[18:19], v[16:17], v[18:19] op_sel:[1,0] op_sel_hi:[0,1]
	v_pk_mul_f32 v[32:33], v[16:17], v[38:39] op_sel:[1,0] op_sel_hi:[0,1]
	v_pk_mul_f32 v[20:21], v[16:17], v[20:21] op_sel:[1,0] op_sel_hi:[0,1]
	v_pk_fma_f32 v[22:23], v[16:17], v[22:23], v[30:31]
	v_pk_fma_f32 v[18:19], v[16:17], v[36:37], v[18:19]
	v_pk_fma_f32 v[28:29], v[16:17], v[28:29], v[32:33]
	v_pk_fma_f32 v[16:17], v[16:17], v[42:43], v[20:21]
	v_pk_fma_f32 v[20:21], v[46:47], v[34:35], v[22:23] op_sel_hi:[0,1,1]
	v_pk_fma_f32 v[18:19], v[46:47], v[24:25], v[18:19] op_sel_hi:[0,1,1]
	v_pk_fma_f32 v[22:23], v[46:47], v[40:41], v[28:29] op_sel_hi:[0,1,1]
	v_pk_fma_f32 v[24:25], v[46:47], v[26:27], v[16:17] op_sel_hi:[0,1,1]
	v_cvt_pk_bf16_f32 v16, v20, v21
	v_cvt_pk_bf16_f32 v17, v18, v19
	v_cvt_pk_bf16_f32 v18, v22, v23
	v_cvt_pk_bf16_f32 v19, v24, v25
	global_store_dwordx4 v[44:45], v[16:19], off offset:2048
	v_add_u32_e32 v84, 16, v84
	v_add_u32_e32 v85, 4, v85
	v_add_u32_e32 v86, 4, v86
	v_add_u32_e32 v87, s70, v87
	s_cbranch_scc0 .LBB0_209
	v_lshl_add_u64 v[8:9], v[8:9], 0, s[24:25]
	v_cmp_lt_u64_e32 vcc, s[60:61], v[8:9]
	s_or_b64 s[8:9], vcc, s[8:9]
	s_andn2_b64 exec, exec, s[8:9]
	s_cbranch_execnz .LBB0_208
